# GEMM K-loops: LDS-DMA loads use SGPR base + 32-bit VGPR offset (34 of 64 per-load 64-bit VALU address adds removed)
# speedup vs baseline: 1.0090x; 1.0026x over previous
.LBB0_70:
	s_add_i32 s35, s18, 2
	s_add_u32 s16, s12, 0x100
	s_addc_u32 s17, s13, 0
	s_cmp_lg_u32 s34, s18
	s_cselect_b32 s22, s16, 0
	s_cselect_b32 s23, s17, 0
	s_add_u32 s18, s10, s22
	s_addc_u32 s19, s11, s23
	s_add_i32 s36, 0, 0x10000
	s_add_u32 s22, s8, s22
	s_addc_u32 s23, s9, s23
	v_lshl_add_u64 v[190:191], v[130:131], 0, s[12:13]
	s_add_i32 m0, s3, 0xc000
	ds_read_b128 v[170:173], v153
	ds_read_b128 v[178:181], v153 offset:2048
	ds_read_b128 v[186:189], v153 offset:4096
	ds_read_b128 v[220:223], v153 offset:6144
	ds_read_b128 v[174:177], v153 offset:1024
	ds_read_b128 v[182:185], v153 offset:3072
	ds_read_b128 v[216:219], v153 offset:5120
	ds_read_b128 v[224:227], v153 offset:7168
	global_load_lds_dwordx4 v[190:191], off
	v_lshl_add_u64 v[190:191], v[150:151], 0, s[12:13]
	s_add_i32 m0, s3, 0xe000
	s_nop 0
	global_load_lds_dwordx4 v[190:191], off
	s_waitcnt lgkmcnt(8)
	s_waitcnt vmcnt(10)
	s_barrier
	s_waitcnt lgkmcnt(4)
	s_setprio 1
	v_mfma_f32_16x16x32_bf16 v[124:127], v[154:157], v[170:173], v[124:127]
	v_mfma_f32_16x16x32_bf16 v[120:123], v[162:165], v[170:173], v[120:123]
	v_mfma_f32_16x16x32_bf16 v[116:119], v[154:157], v[178:181], v[116:119]
	v_mfma_f32_16x16x32_bf16 v[108:111], v[162:165], v[178:181], v[108:111]
	v_mfma_f32_16x16x32_bf16 v[100:103], v[154:157], v[186:189], v[100:103]
	v_mfma_f32_16x16x32_bf16 v[92:95], v[162:165], v[186:189], v[92:95]
	v_mfma_f32_16x16x32_bf16 v[84:87], v[154:157], v[220:223], v[84:87]
	v_mfma_f32_16x16x32_bf16 v[76:79], v[162:165], v[220:223], v[76:79]
	s_waitcnt lgkmcnt(0)
	v_mfma_f32_16x16x32_bf16 v[124:127], v[158:161], v[174:177], v[124:127]
	v_mfma_f32_16x16x32_bf16 v[120:123], v[166:169], v[174:177], v[120:123]
	v_mfma_f32_16x16x32_bf16 v[116:119], v[158:161], v[182:185], v[116:119]
	v_mfma_f32_16x16x32_bf16 v[108:111], v[166:169], v[182:185], v[108:111]
	v_mfma_f32_16x16x32_bf16 v[100:103], v[158:161], v[216:219], v[100:103]
	v_mfma_f32_16x16x32_bf16 v[92:95], v[166:169], v[216:219], v[92:95]
	v_mfma_f32_16x16x32_bf16 v[84:87], v[158:161], v[224:227], v[84:87]
	v_mfma_f32_16x16x32_bf16 v[76:79], v[166:169], v[224:227], v[76:79]
	s_setprio 0
	s_barrier
	s_add_i32 s37, 0, 0x14000
	v_add_u32_e32 v190, s37, v152
	s_add_i32 s12, s36, s26
	ds_read_b128 v[228:231], v190
	ds_read_b128 v[236:239], v190 offset:2048
	ds_read_b128 v[232:235], v190 offset:1024
	ds_read_b128 v[240:243], v190 offset:3072
	v_lshl_add_u64 v[190:191], s[22:23], 0, v[132:133]
	s_mov_b32 m0, s12
	v_lshl_add_u64 v[244:245], s[22:23], 0, v[128:129]
	global_load_lds_dwordx4 v132, s[22:23]
	s_add_i32 m0, s12, 0x2000
	s_nop 0
	global_load_lds_dwordx4 v128, s[22:23]
	s_waitcnt vmcnt(10)
	s_barrier
	s_waitcnt lgkmcnt(2)
	s_setprio 1
	v_mfma_f32_16x16x32_bf16 v[112:115], v[228:231], v[170:173], v[112:115]
	v_mfma_f32_16x16x32_bf16 v[104:107], v[236:239], v[170:173], v[104:107]
	v_mfma_f32_16x16x32_bf16 v[96:99], v[228:231], v[178:181], v[96:99]
	v_mfma_f32_16x16x32_bf16 v[88:91], v[236:239], v[178:181], v[88:91]
	v_mfma_f32_16x16x32_bf16 v[80:83], v[228:231], v[186:189], v[80:83]
	v_mfma_f32_16x16x32_bf16 v[72:75], v[236:239], v[186:189], v[72:75]
	v_mfma_f32_16x16x32_bf16 v[68:71], v[228:231], v[220:223], v[68:71]
	v_mfma_f32_16x16x32_bf16 v[64:67], v[236:239], v[220:223], v[64:67]
	s_waitcnt lgkmcnt(0)
	v_mfma_f32_16x16x32_bf16 v[112:115], v[232:235], v[174:177], v[112:115]
	v_mfma_f32_16x16x32_bf16 v[104:107], v[240:243], v[174:177], v[104:107]
	v_mfma_f32_16x16x32_bf16 v[96:99], v[232:235], v[182:185], v[96:99]
	v_mfma_f32_16x16x32_bf16 v[88:91], v[240:243], v[182:185], v[88:91]
	v_mfma_f32_16x16x32_bf16 v[80:83], v[232:235], v[216:219], v[80:83]
	v_mfma_f32_16x16x32_bf16 v[72:75], v[240:243], v[216:219], v[72:75]
	v_mfma_f32_16x16x32_bf16 v[68:71], v[232:235], v[224:227], v[68:71]
	v_mfma_f32_16x16x32_bf16 v[64:67], v[240:243], v[224:227], v[64:67]
	s_setprio 0
	s_mov_b32 m0, s3
	s_barrier
	ds_read_b128 v[170:173], v153 offset:16384
	ds_read_b128 v[178:181], v153 offset:18432
	ds_read_b128 v[186:189], v153 offset:20480
	ds_read_b128 v[220:223], v153 offset:22528
	ds_read_b128 v[174:177], v153 offset:17408
	ds_read_b128 v[182:185], v153 offset:19456
	ds_read_b128 v[216:219], v153 offset:21504
	ds_read_b128 v[224:227], v153 offset:23552
	global_load_lds_dwordx4 v132, s[18:19]
	s_mov_b32 m0, s5
	s_nop 0
	global_load_lds_dwordx4 v128, s[18:19]
	s_waitcnt vmcnt(10)
	s_barrier
	s_waitcnt lgkmcnt(4)
	s_setprio 1
	v_mfma_f32_16x16x32_bf16 v[60:63], v[154:157], v[170:173], v[60:63]
	v_mfma_f32_16x16x32_bf16 v[56:59], v[162:165], v[170:173], v[56:59]
	v_mfma_f32_16x16x32_bf16 v[52:55], v[154:157], v[178:181], v[52:55]
	v_mfma_f32_16x16x32_bf16 v[44:47], v[162:165], v[178:181], v[44:47]
	v_mfma_f32_16x16x32_bf16 v[36:39], v[154:157], v[186:189], v[36:39]
	v_mfma_f32_16x16x32_bf16 v[28:31], v[162:165], v[186:189], v[28:31]
	v_mfma_f32_16x16x32_bf16 v[20:23], v[154:157], v[220:223], v[20:23]
	v_mfma_f32_16x16x32_bf16 v[12:15], v[162:165], v[220:223], v[12:15]
	s_waitcnt lgkmcnt(0)
	v_mfma_f32_16x16x32_bf16 v[60:63], v[158:161], v[174:177], v[60:63]
	v_mfma_f32_16x16x32_bf16 v[56:59], v[166:169], v[174:177], v[56:59]
	v_mfma_f32_16x16x32_bf16 v[52:55], v[158:161], v[182:185], v[52:55]
	v_mfma_f32_16x16x32_bf16 v[44:47], v[166:169], v[182:185], v[44:47]
	v_mfma_f32_16x16x32_bf16 v[36:39], v[158:161], v[216:219], v[36:39]
	v_mfma_f32_16x16x32_bf16 v[28:31], v[166:169], v[216:219], v[28:31]
	v_mfma_f32_16x16x32_bf16 v[20:23], v[158:161], v[224:227], v[20:23]
	v_mfma_f32_16x16x32_bf16 v[12:15], v[166:169], v[224:227], v[12:15]
	s_setprio 0
	s_barrier
	s_add_u32 s12, s22, s25
	s_addc_u32 s13, s23, 0
	s_add_i32 s22, s37, s26
	v_lshl_add_u64 v[250:251], s[12:13], 0, v[132:133]
	s_mov_b32 m0, s22
	v_lshl_add_u64 v[252:253], s[12:13], 0, v[128:129]
	global_load_lds_dwordx4 v132, s[12:13]
	s_add_i32 m0, s22, 0x2000
	s_nop 0
	global_load_lds_dwordx4 v128, s[12:13]
	v_add_u32_e32 v166, 0x18000, v152
	ds_read_b128 v[154:157], v166
	ds_read_b128 v[158:161], v166 offset:1024
	ds_read_b128 v[162:165], v166 offset:2048
	ds_read_b128 v[166:169], v166 offset:3072
	s_waitcnt vmcnt(10)
	s_barrier
	s_setprio 1
	v_mfma_f32_16x16x32_bf16 v[48:51], v[228:231], v[170:173], v[48:51]
	v_mfma_f32_16x16x32_bf16 v[40:43], v[236:239], v[170:173], v[40:43]
	v_mfma_f32_16x16x32_bf16 v[32:35], v[228:231], v[178:181], v[32:35]
	v_mfma_f32_16x16x32_bf16 v[24:27], v[236:239], v[178:181], v[24:27]
	v_mfma_f32_16x16x32_bf16 v[16:19], v[228:231], v[186:189], v[16:19]
	v_mfma_f32_16x16x32_bf16 v[8:11], v[236:239], v[186:189], v[8:11]
	v_mfma_f32_16x16x32_bf16 v[4:7], v[228:231], v[220:223], v[4:7]
	v_mfma_f32_16x16x32_bf16 v[0:3], v[236:239], v[220:223], v[0:3]
	v_mfma_f32_16x16x32_bf16 v[48:51], v[232:235], v[174:177], v[48:51]
	v_mfma_f32_16x16x32_bf16 v[40:43], v[240:243], v[174:177], v[40:43]
	v_mfma_f32_16x16x32_bf16 v[32:35], v[232:235], v[182:185], v[32:35]
	v_mfma_f32_16x16x32_bf16 v[24:27], v[240:243], v[182:185], v[24:27]
	v_mfma_f32_16x16x32_bf16 v[16:19], v[232:235], v[216:219], v[16:19]
	v_mfma_f32_16x16x32_bf16 v[8:11], v[240:243], v[216:219], v[8:11]
	v_mfma_f32_16x16x32_bf16 v[4:7], v[232:235], v[224:227], v[4:7]
	v_mfma_f32_16x16x32_bf16 v[0:3], v[240:243], v[224:227], v[0:3]
	s_setprio 0
	s_add_i32 s22, 0, 0x18000
	s_barrier
	s_add_u32 s12, s18, s25
	s_addc_u32 s13, s19, 0
	s_mov_b32 m0, s27
	ds_read_b128 v[170:173], v153 offset:32768
	ds_read_b128 v[178:181], v153 offset:34816
	ds_read_b128 v[186:189], v153 offset:36864
	ds_read_b128 v[220:223], v153 offset:38912
	ds_read_b128 v[174:177], v153 offset:33792
	ds_read_b128 v[182:185], v153 offset:35840
	ds_read_b128 v[216:219], v153 offset:37888
	ds_read_b128 v[224:227], v153 offset:39936
	global_load_lds_dwordx4 v132, s[12:13]
	s_mov_b32 m0, s28
	s_nop 0
	global_load_lds_dwordx4 v128, s[12:13]
	s_waitcnt lgkmcnt(8)
	s_waitcnt vmcnt(10)
	s_barrier
	s_waitcnt lgkmcnt(4)
	s_setprio 1
	v_mfma_f32_16x16x32_bf16 v[124:127], v[154:157], v[170:173], v[124:127]
	v_mfma_f32_16x16x32_bf16 v[120:123], v[162:165], v[170:173], v[120:123]
	v_mfma_f32_16x16x32_bf16 v[116:119], v[154:157], v[178:181], v[116:119]
	v_mfma_f32_16x16x32_bf16 v[108:111], v[162:165], v[178:181], v[108:111]
	v_mfma_f32_16x16x32_bf16 v[100:103], v[154:157], v[186:189], v[100:103]
	v_mfma_f32_16x16x32_bf16 v[92:95], v[162:165], v[186:189], v[92:95]
	v_mfma_f32_16x16x32_bf16 v[84:87], v[154:157], v[220:223], v[84:87]
	v_mfma_f32_16x16x32_bf16 v[76:79], v[162:165], v[220:223], v[76:79]
	s_waitcnt lgkmcnt(0)
	v_mfma_f32_16x16x32_bf16 v[124:127], v[158:161], v[174:177], v[124:127]
	v_mfma_f32_16x16x32_bf16 v[120:123], v[166:169], v[174:177], v[120:123]
	v_mfma_f32_16x16x32_bf16 v[116:119], v[158:161], v[182:185], v[116:119]
	v_mfma_f32_16x16x32_bf16 v[108:111], v[166:169], v[182:185], v[108:111]
	v_mfma_f32_16x16x32_bf16 v[100:103], v[158:161], v[216:219], v[100:103]
	v_mfma_f32_16x16x32_bf16 v[92:95], v[166:169], v[216:219], v[92:95]
	v_mfma_f32_16x16x32_bf16 v[84:87], v[158:161], v[224:227], v[84:87]
	v_mfma_f32_16x16x32_bf16 v[76:79], v[166:169], v[224:227], v[76:79]
	s_setprio 0
	s_barrier
	s_add_i32 s12, 0, 0x1c000
	s_add_i32 s13, s22, s26
	v_add_u32_e32 v200, s12, v152
	v_lshl_add_u64 v[190:191], v[190:191], 0, s[66:67]
	s_mov_b32 m0, s13
	ds_read_b128 v[228:231], v200
	ds_read_b128 v[236:239], v200 offset:2048
	ds_read_b128 v[232:235], v200 offset:1024
	ds_read_b128 v[240:243], v200 offset:3072
	global_load_lds_dwordx4 v[190:191], off
	v_lshl_add_u64 v[190:191], v[244:245], 0, s[66:67]
	s_add_i32 m0, s13, 0x2000
	s_nop 0
	global_load_lds_dwordx4 v[190:191], off
	s_waitcnt vmcnt(10)
	s_barrier
	s_waitcnt lgkmcnt(2)
	s_setprio 1
	v_mfma_f32_16x16x32_bf16 v[112:115], v[228:231], v[170:173], v[112:115]
	v_mfma_f32_16x16x32_bf16 v[104:107], v[236:239], v[170:173], v[104:107]
	v_mfma_f32_16x16x32_bf16 v[96:99], v[228:231], v[178:181], v[96:99]
	v_mfma_f32_16x16x32_bf16 v[88:91], v[236:239], v[178:181], v[88:91]
	v_mfma_f32_16x16x32_bf16 v[80:83], v[228:231], v[186:189], v[80:83]
	v_mfma_f32_16x16x32_bf16 v[72:75], v[236:239], v[186:189], v[72:75]
	v_mfma_f32_16x16x32_bf16 v[68:71], v[228:231], v[220:223], v[68:71]
	v_mfma_f32_16x16x32_bf16 v[64:67], v[236:239], v[220:223], v[64:67]
	s_waitcnt lgkmcnt(0)
	v_mfma_f32_16x16x32_bf16 v[112:115], v[232:235], v[174:177], v[112:115]
	v_mfma_f32_16x16x32_bf16 v[104:107], v[240:243], v[174:177], v[104:107]
	v_mfma_f32_16x16x32_bf16 v[96:99], v[232:235], v[182:185], v[96:99]
	v_mfma_f32_16x16x32_bf16 v[88:91], v[240:243], v[182:185], v[88:91]
	v_mfma_f32_16x16x32_bf16 v[80:83], v[232:235], v[216:219], v[80:83]
	v_mfma_f32_16x16x32_bf16 v[72:75], v[240:243], v[216:219], v[72:75]
	v_mfma_f32_16x16x32_bf16 v[68:71], v[232:235], v[224:227], v[68:71]
	v_mfma_f32_16x16x32_bf16 v[64:67], v[240:243], v[224:227], v[64:67]
	s_setprio 0
	s_mov_b32 m0, s30
	s_barrier
	ds_read_b128 v[170:173], v153 offset:49152
	ds_read_b128 v[178:181], v153 offset:51200
	ds_read_b128 v[186:189], v153 offset:53248
	ds_read_b128 v[220:223], v153 offset:55296
	ds_read_b128 v[174:177], v153 offset:50176
	ds_read_b128 v[182:185], v153 offset:52224
	ds_read_b128 v[216:219], v153 offset:54272
	ds_read_b128 v[224:227], v153 offset:56320
	s_add_u32 s98, s18, 0x80
	s_addc_u32 s99, s19, 0
	global_load_lds_dwordx4 v132, s[98:99]
	s_mov_b32 m0, s31
	s_nop 0
	global_load_lds_dwordx4 v128, s[98:99]
	s_waitcnt vmcnt(10)
	s_barrier
	s_waitcnt lgkmcnt(4)
	s_setprio 1
	v_mfma_f32_16x16x32_bf16 v[60:63], v[154:157], v[170:173], v[60:63]
	v_mfma_f32_16x16x32_bf16 v[56:59], v[162:165], v[170:173], v[56:59]
	v_mfma_f32_16x16x32_bf16 v[52:55], v[154:157], v[178:181], v[52:55]
	v_mfma_f32_16x16x32_bf16 v[44:47], v[162:165], v[178:181], v[44:47]
	v_mfma_f32_16x16x32_bf16 v[36:39], v[154:157], v[186:189], v[36:39]
	v_mfma_f32_16x16x32_bf16 v[28:31], v[162:165], v[186:189], v[28:31]
	v_mfma_f32_16x16x32_bf16 v[20:23], v[154:157], v[220:223], v[20:23]
	v_mfma_f32_16x16x32_bf16 v[12:15], v[162:165], v[220:223], v[12:15]
	s_waitcnt lgkmcnt(0)
	v_mfma_f32_16x16x32_bf16 v[60:63], v[158:161], v[174:177], v[60:63]
	v_mfma_f32_16x16x32_bf16 v[56:59], v[166:169], v[174:177], v[56:59]
	v_mfma_f32_16x16x32_bf16 v[52:55], v[158:161], v[182:185], v[52:55]
	v_mfma_f32_16x16x32_bf16 v[44:47], v[166:169], v[182:185], v[44:47]
	v_mfma_f32_16x16x32_bf16 v[36:39], v[158:161], v[216:219], v[36:39]
	v_mfma_f32_16x16x32_bf16 v[28:31], v[166:169], v[216:219], v[28:31]
	v_mfma_f32_16x16x32_bf16 v[20:23], v[158:161], v[224:227], v[20:23]
	v_mfma_f32_16x16x32_bf16 v[12:15], v[166:169], v[224:227], v[12:15]
	s_setprio 0
	s_barrier
	s_add_i32 s12, s12, s26
	v_lshl_add_u64 v[154:155], v[250:251], 0, s[66:67]
	s_mov_b32 m0, s12
	s_nop 0
	global_load_lds_dwordx4 v[154:155], off
	v_lshl_add_u64 v[154:155], v[252:253], 0, s[66:67]
	s_add_i32 m0, s12, 0x2000
	s_nop 0
	global_load_lds_dwordx4 v[154:155], off
	v_add_u32_e32 v166, 0x10000, v152
	ds_read_b128 v[154:157], v166
	ds_read_b128 v[158:161], v166 offset:1024
	ds_read_b128 v[162:165], v166 offset:2048
	ds_read_b128 v[166:169], v166 offset:3072
	s_waitcnt vmcnt(10)
	s_barrier
	s_setprio 1
	v_mfma_f32_16x16x32_bf16 v[48:51], v[228:231], v[170:173], v[48:51]
	v_mfma_f32_16x16x32_bf16 v[40:43], v[236:239], v[170:173], v[40:43]
	v_mfma_f32_16x16x32_bf16 v[32:35], v[228:231], v[178:181], v[32:35]
	v_mfma_f32_16x16x32_bf16 v[24:27], v[236:239], v[178:181], v[24:27]
	v_mfma_f32_16x16x32_bf16 v[16:19], v[228:231], v[186:189], v[16:19]
	v_mfma_f32_16x16x32_bf16 v[8:11], v[236:239], v[186:189], v[8:11]
	v_mfma_f32_16x16x32_bf16 v[4:7], v[228:231], v[220:223], v[4:7]
	v_mfma_f32_16x16x32_bf16 v[0:3], v[236:239], v[220:223], v[0:3]
	v_mfma_f32_16x16x32_bf16 v[48:51], v[232:235], v[174:177], v[48:51]
	v_mfma_f32_16x16x32_bf16 v[40:43], v[240:243], v[174:177], v[40:43]
	v_mfma_f32_16x16x32_bf16 v[32:35], v[232:235], v[182:185], v[32:35]
	v_mfma_f32_16x16x32_bf16 v[24:27], v[240:243], v[182:185], v[24:27]
	v_mfma_f32_16x16x32_bf16 v[16:19], v[232:235], v[216:219], v[16:19]
	v_mfma_f32_16x16x32_bf16 v[8:11], v[240:243], v[216:219], v[8:11]
	v_mfma_f32_16x16x32_bf16 v[4:7], v[232:235], v[224:227], v[4:7]
	v_mfma_f32_16x16x32_bf16 v[0:3], v[240:243], v[224:227], v[0:3]
	s_setprio 0
	s_cmp_ge_u32 s35, s29
	s_mov_b64 s[12:13], s[16:17]
	s_mov_b32 s18, s35
	s_barrier
	s_cbranch_scc0 .LBB0_70
	s_waitcnt lgkmcnt(0)
	s_and_b64 s[6:7], s[6:7], exec
	v_mov_b32_e32 v128, v135
	s_mov_b64 s[6:7], s[0:1]
	s_load_dwordx2 s[6:7], s[6:7], 0x88
	s_cselect_b32 s3, 0x2000, 0
	v_readfirstlane_b32 s5, v128
	v_lshrrev_b32_e32 v129, 2, v128
	v_cvt_pk_bf16_f32 v104, v104, v105
	s_waitcnt lgkmcnt(0)
	s_add_u32 s6, s6, 0xfea4400
	s_addc_u32 s7, s7, 0
	s_ashr_i32 s8, s5, 2
	s_andn2_b32 s8, s8, 63
	v_and_or_b32 v128, v128, 15, s8
	s_lshr_b32 s5, s5, 1
	v_lshl_add_u32 v150, s2, 8, v128
	s_lshl_b32 s2, s4, s15
	s_and_b32 s5, s5, 0x60
	s_add_i32 s2, s2, s3
	v_and_or_b32 v132, v129, 12, s5
	v_add_u32_e32 v130, s2, v150
	v_mov_b64_e32 v[128:129], s[6:7]
	v_mad_i64_i32 v[130:131], s[4:5], v130, s96, v[128:129]
	s_lshl_b32 s58, s58, 9
	v_lshl_add_u64 v[130:131], v[130:131], 0, s[58:59]
	v_lshlrev_b32_e32 v132, 1, v132
	v_lshl_add_u64 v[130:131], v[130:131], 0, v[132:133]
	v_cvt_pk_bf16_f32 v105, v106, v107
	global_store_dwordx2 v[130:131], v[104:105], off offset:1824
	v_add3_u32 v104, s2, 16, v150
	v_mad_i64_i32 v[104:105], s[4:5], v104, s96, v[128:129]
	v_lshl_add_u64 v[104:105], v[104:105], 0, s[58:59]
	v_lshl_add_u64 v[104:105], v[104:105], 0, v[132:133]
	v_cvt_pk_bf16_f32 v88, v88, v89
	v_cvt_pk_bf16_f32 v89, v90, v91
	global_store_dwordx2 v[104:105], v[88:89], off offset:1824
	v_add3_u32 v88, s2, 32, v150
	v_mad_i64_i32 v[88:89], s[4:5], v88, s96, v[128:129]
	v_lshl_add_u64 v[88:89], v[88:89], 0, s[58:59]
	v_lshl_add_u64 v[88:89], v[88:89], 0, v[132:133]
	v_cvt_pk_bf16_f32 v72, v72, v73
	v_cvt_pk_bf16_f32 v73, v74, v75
	global_store_dwordx2 v[88:89], v[72:73], off offset:1824
	v_add3_u32 v72, s2, 48, v150
	v_mad_i64_i32 v[72:73], s[4:5], v72, s96, v[128:129]
	v_lshl_add_u64 v[72:73], v[72:73], 0, s[58:59]
	v_lshl_add_u64 v[72:73], v[72:73], 0, v[132:133]
	v_cvt_pk_bf16_f32 v64, v64, v65
	s_add_i32 s3, s2, 0x80
	v_cvt_pk_bf16_f32 v65, v66, v67
	global_store_dwordx2 v[72:73], v[64:65], off offset:1824
	v_add_u32_e32 v64, s3, v150
	v_mad_i64_i32 v[64:65], s[4:5], v64, s96, v[128:129]
	v_lshl_add_u64 v[64:65], v[64:65], 0, s[58:59]
	v_lshl_add_u64 v[64:65], v[64:65], 0, v[132:133]
	v_cvt_pk_bf16_f32 v40, v40, v41
	s_add_i32 s3, s2, 0x90
	v_cvt_pk_bf16_f32 v41, v42, v43
	global_store_dwordx2 v[64:65], v[40:41], off offset:1824
	v_add_u32_e32 v40, s3, v150
	v_mad_i64_i32 v[40:41], s[4:5], v40, s96, v[128:129]
	v_lshl_add_u64 v[40:41], v[40:41], 0, s[58:59]
	v_lshl_add_u64 v[40:41], v[40:41], 0, v[132:133]
	v_cvt_pk_bf16_f32 v24, v24, v25
	s_add_i32 s3, s2, 0xa0
	v_cvt_pk_bf16_f32 v25, v26, v27
	global_store_dwordx2 v[40:41], v[24:25], off offset:1824
	v_add_u32_e32 v24, s3, v150
	v_mad_i64_i32 v[24:25], s[4:5], v24, s96, v[128:129]
	v_lshl_add_u64 v[24:25], v[24:25], 0, s[58:59]
	v_lshl_add_u64 v[24:25], v[24:25], 0, v[132:133]
	v_cvt_pk_bf16_f32 v8, v8, v9
	s_addk_i32 s2, 0xb0
	v_cvt_pk_bf16_f32 v9, v10, v11
	global_store_dwordx2 v[24:25], v[8:9], off offset:1824
	v_add_u32_e32 v8, s2, v150
	v_mad_i64_i32 v[8:9], s[2:3], v8, s96, v[128:129]
	v_lshl_add_u64 v[8:9], v[8:9], 0, s[58:59]
	v_cvt_pk_bf16_f32 v106, v116, v117
	v_cvt_pk_bf16_f32 v107, v118, v119
	v_cvt_pk_bf16_f32 v90, v100, v101
	v_cvt_pk_bf16_f32 v91, v102, v103
	v_cvt_pk_bf16_f32 v74, v84, v85
	v_cvt_pk_bf16_f32 v75, v86, v87
	v_cvt_pk_bf16_f32 v42, v52, v53
	v_cvt_pk_bf16_f32 v43, v54, v55
	v_cvt_pk_bf16_f32 v26, v36, v37
	v_cvt_pk_bf16_f32 v27, v38, v39
	v_lshl_add_u64 v[8:9], v[8:9], 0, v[132:133]
	v_cvt_pk_bf16_f32 v10, v20, v21
	v_cvt_pk_bf16_f32 v11, v22, v23
	v_cvt_pk_bf16_f32 v124, v124, v125
	v_cvt_pk_bf16_f32 v125, v126, v127
	global_store_dwordx2 v[130:131], v[124:125], off offset:1536
	v_cvt_pk_bf16_f32 v120, v120, v121
	v_cvt_pk_bf16_f32 v121, v122, v123
	global_store_dwordx2 v[130:131], v[120:121], off offset:1568
	v_cvt_pk_bf16_f32 v112, v112, v113
	v_cvt_pk_bf16_f32 v113, v114, v115
	global_store_dwordx2 v[130:131], v[112:113], off offset:1792
	global_store_dwordx2 v[104:105], v[106:107], off offset:1536
	v_cvt_pk_bf16_f32 v106, v108, v109
	v_cvt_pk_bf16_f32 v107, v110, v111
	global_store_dwordx2 v[104:105], v[106:107], off offset:1568
	v_cvt_pk_bf16_f32 v96, v96, v97
	v_cvt_pk_bf16_f32 v97, v98, v99
	global_store_dwordx2 v[104:105], v[96:97], off offset:1792
	global_store_dwordx2 v[88:89], v[90:91], off offset:1536
	v_cvt_pk_bf16_f32 v90, v92, v93
	v_cvt_pk_bf16_f32 v91, v94, v95
	global_store_dwordx2 v[88:89], v[90:91], off offset:1568
	v_cvt_pk_bf16_f32 v80, v80, v81
	v_cvt_pk_bf16_f32 v81, v82, v83
	global_store_dwordx2 v[88:89], v[80:81], off offset:1792
	global_store_dwordx2 v[72:73], v[74:75], off offset:1536
	v_cvt_pk_bf16_f32 v74, v76, v77
	v_cvt_pk_bf16_f32 v75, v78, v79
	global_store_dwordx2 v[72:73], v[74:75], off offset:1568
	v_cvt_pk_bf16_f32 v68, v68, v69
	v_cvt_pk_bf16_f32 v69, v70, v71
	global_store_dwordx2 v[72:73], v[68:69], off offset:1792
	v_cvt_pk_bf16_f32 v60, v60, v61
	v_cvt_pk_bf16_f32 v61, v62, v63
	global_store_dwordx2 v[64:65], v[60:61], off offset:1536
	v_cvt_pk_bf16_f32 v56, v56, v57
	v_cvt_pk_bf16_f32 v57, v58, v59
	global_store_dwordx2 v[64:65], v[56:57], off offset:1568
	v_cvt_pk_bf16_f32 v48, v48, v49
	v_cvt_pk_bf16_f32 v49, v50, v51
	global_store_dwordx2 v[64:65], v[48:49], off offset:1792
	global_store_dwordx2 v[40:41], v[42:43], off offset:1536
	v_cvt_pk_bf16_f32 v42, v44, v45
	v_cvt_pk_bf16_f32 v43, v46, v47
	global_store_dwordx2 v[40:41], v[42:43], off offset:1568
	v_cvt_pk_bf16_f32 v32, v32, v33
	v_cvt_pk_bf16_f32 v33, v34, v35
	global_store_dwordx2 v[40:41], v[32:33], off offset:1792
	global_store_dwordx2 v[24:25], v[26:27], off offset:1536
	v_cvt_pk_bf16_f32 v26, v28, v29
	v_cvt_pk_bf16_f32 v27, v30, v31
	global_store_dwordx2 v[24:25], v[26:27], off offset:1568
	v_cvt_pk_bf16_f32 v16, v16, v17
	v_cvt_pk_bf16_f32 v17, v18, v19
	global_store_dwordx2 v[24:25], v[16:17], off offset:1792
	global_store_dwordx2 v[8:9], v[10:11], off offset:1536
	v_cvt_pk_bf16_f32 v10, v12, v13
	v_cvt_pk_bf16_f32 v11, v14, v15
	global_store_dwordx2 v[8:9], v[10:11], off offset:1568
	v_cvt_pk_bf16_f32 v4, v4, v5
	v_cvt_pk_bf16_f32 v5, v6, v7
	global_store_dwordx2 v[8:9], v[4:5], off offset:1792
	v_cvt_pk_bf16_f32 v0, v0, v1
	v_cvt_pk_bf16_f32 v1, v2, v3
	global_store_dwordx2 v[8:9], v[0:1], off offset:1824
	s_waitcnt vmcnt(0)
	s_cmpk_lt_u32 s14, 0x100
	s_cbranch_scc0 .LBB0_73
	s_barrier

.LBB0_145:
	s_add_u32 s6, s2, 0xfffc0080
	s_addc_u32 s7, s3, -1
	s_add_i32 s29, 0, 0x10000
	s_cmp_eq_u32 s28, 12
	s_cselect_b32 s11, s9, s7
	s_cselect_b32 s10, s12, s6
	s_cselect_b32 s7, s13, s27
	s_cselect_b32 s6, s17, s19
	s_add_i32 m0, s50, 0xc000
	ds_read_b128 v[170:173], v216
	ds_read_b128 v[178:181], v216 offset:2048
	ds_read_b128 v[186:189], v216 offset:4096
	ds_read_b128 v[222:225], v216 offset:6144
	ds_read_b128 v[174:177], v216 offset:1024
	ds_read_b128 v[182:185], v216 offset:3072
	ds_read_b128 v[218:221], v216 offset:5120
	ds_read_b128 v[226:229], v216 offset:7168
	global_load_lds_dwordx4 v154, s[2:3]
	s_add_i32 m0, s50, 0xe000
	s_nop 0
	global_load_lds_dwordx4 v156, s[2:3]
	s_waitcnt lgkmcnt(8)
	s_waitcnt vmcnt(10)
	s_barrier
	s_waitcnt lgkmcnt(4)
	s_setprio 1
	v_mfma_f32_16x16x32_bf16 v[124:127], v[128:131], v[170:173], v[124:127]
	v_mfma_f32_16x16x32_bf16 v[120:123], v[162:165], v[170:173], v[120:123]
	v_mfma_f32_16x16x32_bf16 v[108:111], v[128:131], v[178:181], v[108:111]
	v_mfma_f32_16x16x32_bf16 v[104:107], v[162:165], v[178:181], v[104:107]
	v_mfma_f32_16x16x32_bf16 v[92:95], v[128:131], v[186:189], v[92:95]
	v_mfma_f32_16x16x32_bf16 v[88:91], v[162:165], v[186:189], v[88:91]
	v_mfma_f32_16x16x32_bf16 v[76:79], v[128:131], v[222:225], v[76:79]
	v_mfma_f32_16x16x32_bf16 v[72:75], v[162:165], v[222:225], v[72:75]
	s_waitcnt lgkmcnt(0)
	v_mfma_f32_16x16x32_bf16 v[124:127], v[158:161], v[174:177], v[124:127]
	v_mfma_f32_16x16x32_bf16 v[120:123], v[166:169], v[174:177], v[120:123]
	v_mfma_f32_16x16x32_bf16 v[108:111], v[158:161], v[182:185], v[108:111]
	v_mfma_f32_16x16x32_bf16 v[104:107], v[166:169], v[182:185], v[104:107]
	v_mfma_f32_16x16x32_bf16 v[92:95], v[158:161], v[218:221], v[92:95]
	v_mfma_f32_16x16x32_bf16 v[88:91], v[166:169], v[218:221], v[88:91]
	v_mfma_f32_16x16x32_bf16 v[76:79], v[158:161], v[226:229], v[76:79]
	v_mfma_f32_16x16x32_bf16 v[72:75], v[166:169], v[226:229], v[72:75]
	s_setprio 0
	s_barrier
	s_add_i32 s34, 0, 0x14000
	s_add_i32 s29, s29, s15
	v_add_u32_e32 v132, s34, v215
	s_mov_b32 m0, s29
	ds_read_b128 v[230:233], v132
	ds_read_b128 v[238:241], v132 offset:2048
	ds_read_b128 v[234:237], v132 offset:1024
	ds_read_b128 v[242:245], v132 offset:3072
	global_load_lds_dwordx4 v150, s[6:7]
	s_add_i32 m0, s29, 0x2000
	s_nop 0
	global_load_lds_dwordx4 v152, s[6:7]
	s_waitcnt vmcnt(10)
	s_barrier
	s_waitcnt lgkmcnt(2)
	s_setprio 1
	v_mfma_f32_16x16x32_bf16 v[116:119], v[230:233], v[170:173], v[116:119]
	v_mfma_f32_16x16x32_bf16 v[112:115], v[238:241], v[170:173], v[112:115]
	v_mfma_f32_16x16x32_bf16 v[100:103], v[230:233], v[178:181], v[100:103]
	v_mfma_f32_16x16x32_bf16 v[96:99], v[238:241], v[178:181], v[96:99]
	v_mfma_f32_16x16x32_bf16 v[84:87], v[230:233], v[186:189], v[84:87]
	v_mfma_f32_16x16x32_bf16 v[80:83], v[238:241], v[186:189], v[80:83]
	v_mfma_f32_16x16x32_bf16 v[68:71], v[230:233], v[222:225], v[68:71]
	v_mfma_f32_16x16x32_bf16 v[64:67], v[238:241], v[222:225], v[64:67]
	s_waitcnt lgkmcnt(0)
	v_mfma_f32_16x16x32_bf16 v[116:119], v[234:237], v[174:177], v[116:119]
	v_mfma_f32_16x16x32_bf16 v[112:115], v[242:245], v[174:177], v[112:115]
	v_mfma_f32_16x16x32_bf16 v[100:103], v[234:237], v[182:185], v[100:103]
	v_mfma_f32_16x16x32_bf16 v[96:99], v[242:245], v[182:185], v[96:99]
	v_mfma_f32_16x16x32_bf16 v[84:87], v[234:237], v[218:221], v[84:87]
	v_mfma_f32_16x16x32_bf16 v[80:83], v[242:245], v[218:221], v[80:83]
	v_mfma_f32_16x16x32_bf16 v[68:71], v[234:237], v[226:229], v[68:71]
	v_mfma_f32_16x16x32_bf16 v[64:67], v[242:245], v[226:229], v[64:67]
	s_setprio 0
	s_mov_b32 m0, s50
	v_lshl_add_u64 v[248:249], s[10:11], 0, v[150:151]
	s_barrier
	ds_read_b128 v[170:173], v216 offset:16384
	ds_read_b128 v[178:181], v216 offset:18432
	ds_read_b128 v[186:189], v216 offset:20480
	ds_read_b128 v[222:225], v216 offset:22528
	ds_read_b128 v[174:177], v216 offset:17408
	ds_read_b128 v[182:185], v216 offset:19456
	ds_read_b128 v[218:221], v216 offset:21504
	ds_read_b128 v[226:229], v216 offset:23552
	global_load_lds_dwordx4 v150, s[10:11]
	v_lshl_add_u64 v[250:251], s[10:11], 0, v[152:153]
	s_mov_b32 m0, s51
	s_nop 0
	global_load_lds_dwordx4 v152, s[10:11]
	s_waitcnt vmcnt(10)
	s_barrier
	s_waitcnt lgkmcnt(4)
	s_setprio 1
	v_mfma_f32_16x16x32_bf16 v[60:63], v[128:131], v[170:173], v[60:63]
	v_mfma_f32_16x16x32_bf16 v[56:59], v[162:165], v[170:173], v[56:59]
	v_mfma_f32_16x16x32_bf16 v[44:47], v[128:131], v[178:181], v[44:47]
	v_mfma_f32_16x16x32_bf16 v[40:43], v[162:165], v[178:181], v[40:43]
	v_mfma_f32_16x16x32_bf16 v[28:31], v[128:131], v[186:189], v[28:31]
	v_mfma_f32_16x16x32_bf16 v[24:27], v[162:165], v[186:189], v[24:27]
	v_mfma_f32_16x16x32_bf16 v[12:15], v[128:131], v[222:225], v[12:15]
	v_mfma_f32_16x16x32_bf16 v[8:11], v[162:165], v[222:225], v[8:11]
	s_waitcnt lgkmcnt(0)
	v_mfma_f32_16x16x32_bf16 v[60:63], v[158:161], v[174:177], v[60:63]
	v_mfma_f32_16x16x32_bf16 v[56:59], v[166:169], v[174:177], v[56:59]
	v_mfma_f32_16x16x32_bf16 v[44:47], v[158:161], v[182:185], v[44:47]
	v_mfma_f32_16x16x32_bf16 v[40:43], v[166:169], v[182:185], v[40:43]
	v_mfma_f32_16x16x32_bf16 v[28:31], v[158:161], v[218:221], v[28:31]
	v_mfma_f32_16x16x32_bf16 v[24:27], v[166:169], v[218:221], v[24:27]
	v_mfma_f32_16x16x32_bf16 v[12:15], v[158:161], v[226:229], v[12:15]
	v_mfma_f32_16x16x32_bf16 v[8:11], v[166:169], v[226:229], v[8:11]
	s_setprio 0
	s_barrier
	s_add_u32 s30, s6, 0x40000
	s_addc_u32 s31, s7, 0
	s_add_i32 s29, s34, s15
	s_mov_b32 m0, s29
	s_nop 0
	global_load_lds_dwordx4 v150, s[30:31]
	s_add_i32 m0, s29, 0x2000
	s_nop 0
	global_load_lds_dwordx4 v152, s[30:31]
	v_add_u32_e32 v166, 0x18000, v215
	ds_read_b128 v[128:131], v166
	ds_read_b128 v[158:161], v166 offset:1024
	ds_read_b128 v[162:165], v166 offset:2048
	ds_read_b128 v[166:169], v166 offset:3072
	s_waitcnt vmcnt(10)
	s_barrier
	s_setprio 1
	v_mfma_f32_16x16x32_bf16 v[52:55], v[230:233], v[170:173], v[52:55]
	v_mfma_f32_16x16x32_bf16 v[48:51], v[238:241], v[170:173], v[48:51]
	v_mfma_f32_16x16x32_bf16 v[36:39], v[230:233], v[178:181], v[36:39]
	v_mfma_f32_16x16x32_bf16 v[32:35], v[238:241], v[178:181], v[32:35]
	v_mfma_f32_16x16x32_bf16 v[20:23], v[230:233], v[186:189], v[20:23]
	v_mfma_f32_16x16x32_bf16 v[16:19], v[238:241], v[186:189], v[16:19]
	v_mfma_f32_16x16x32_bf16 v[4:7], v[230:233], v[222:225], v[4:7]
	v_mfma_f32_16x16x32_bf16 v[0:3], v[238:241], v[222:225], v[0:3]
	v_mfma_f32_16x16x32_bf16 v[52:55], v[234:237], v[174:177], v[52:55]
	v_mfma_f32_16x16x32_bf16 v[48:51], v[242:245], v[174:177], v[48:51]
	v_mfma_f32_16x16x32_bf16 v[36:39], v[234:237], v[182:185], v[36:39]
	v_mfma_f32_16x16x32_bf16 v[32:35], v[242:245], v[182:185], v[32:35]
	v_mfma_f32_16x16x32_bf16 v[20:23], v[234:237], v[218:221], v[20:23]
	v_mfma_f32_16x16x32_bf16 v[16:19], v[242:245], v[218:221], v[16:19]
	v_mfma_f32_16x16x32_bf16 v[4:7], v[234:237], v[226:229], v[4:7]
	v_mfma_f32_16x16x32_bf16 v[0:3], v[242:245], v[226:229], v[0:3]
	s_setprio 0
	s_add_i32 s29, 0, 0x18000
	s_barrier
	s_add_u32 s10, s10, 0x40000
	s_addc_u32 s11, s11, 0
	s_mov_b32 m0, s36
	ds_read_b128 v[170:173], v216 offset:32768
	ds_read_b128 v[178:181], v216 offset:34816
	ds_read_b128 v[186:189], v216 offset:36864
	ds_read_b128 v[222:225], v216 offset:38912
	ds_read_b128 v[174:177], v216 offset:33792
	ds_read_b128 v[182:185], v216 offset:35840
	ds_read_b128 v[218:221], v216 offset:37888
	ds_read_b128 v[226:229], v216 offset:39936
	global_load_lds_dwordx4 v150, s[10:11]
	s_mov_b32 m0, s37
	s_nop 0
	global_load_lds_dwordx4 v152, s[10:11]
	s_waitcnt lgkmcnt(8)
	s_waitcnt vmcnt(10)
	s_barrier
	s_waitcnt lgkmcnt(4)
	s_setprio 1
	v_mfma_f32_16x16x32_bf16 v[124:127], v[128:131], v[170:173], v[124:127]
	v_mfma_f32_16x16x32_bf16 v[120:123], v[162:165], v[170:173], v[120:123]
	v_mfma_f32_16x16x32_bf16 v[108:111], v[128:131], v[178:181], v[108:111]
	v_mfma_f32_16x16x32_bf16 v[104:107], v[162:165], v[178:181], v[104:107]
	v_mfma_f32_16x16x32_bf16 v[92:95], v[128:131], v[186:189], v[92:95]
	v_mfma_f32_16x16x32_bf16 v[88:91], v[162:165], v[186:189], v[88:91]
	v_mfma_f32_16x16x32_bf16 v[76:79], v[128:131], v[222:225], v[76:79]
	v_mfma_f32_16x16x32_bf16 v[72:75], v[162:165], v[222:225], v[72:75]
	s_waitcnt lgkmcnt(0)
	v_mfma_f32_16x16x32_bf16 v[124:127], v[158:161], v[174:177], v[124:127]
	v_mfma_f32_16x16x32_bf16 v[120:123], v[166:169], v[174:177], v[120:123]
	v_mfma_f32_16x16x32_bf16 v[108:111], v[158:161], v[182:185], v[108:111]
	v_mfma_f32_16x16x32_bf16 v[104:107], v[166:169], v[182:185], v[104:107]
	v_mfma_f32_16x16x32_bf16 v[92:95], v[158:161], v[218:221], v[92:95]
	v_mfma_f32_16x16x32_bf16 v[88:91], v[166:169], v[218:221], v[88:91]
	v_mfma_f32_16x16x32_bf16 v[76:79], v[158:161], v[226:229], v[76:79]
	v_mfma_f32_16x16x32_bf16 v[72:75], v[166:169], v[226:229], v[72:75]
	s_setprio 0
	s_barrier
	s_add_i32 s10, 0, 0x1c000
	s_add_i32 s11, s29, s15
	v_add_u32_e32 v132, s10, v215
	s_mov_b32 m0, s11
	ds_read_b128 v[230:233], v132
	ds_read_b128 v[238:241], v132 offset:2048
	ds_read_b128 v[234:237], v132 offset:1024
	ds_read_b128 v[242:245], v132 offset:3072
	s_add_u32 s98, s6, 0x80
	s_addc_u32 s99, s7, 0
	global_load_lds_dwordx4 v150, s[98:99]
	s_add_i32 m0, s11, 0x2000
	s_nop 0
	global_load_lds_dwordx4 v152, s[98:99]
	s_waitcnt vmcnt(10)
	s_barrier
	s_waitcnt lgkmcnt(2)
	s_setprio 1
	v_mfma_f32_16x16x32_bf16 v[116:119], v[230:233], v[170:173], v[116:119]
	v_mfma_f32_16x16x32_bf16 v[112:115], v[238:241], v[170:173], v[112:115]
	v_mfma_f32_16x16x32_bf16 v[100:103], v[230:233], v[178:181], v[100:103]
	v_mfma_f32_16x16x32_bf16 v[96:99], v[238:241], v[178:181], v[96:99]
	v_mfma_f32_16x16x32_bf16 v[84:87], v[230:233], v[186:189], v[84:87]
	v_mfma_f32_16x16x32_bf16 v[80:83], v[238:241], v[186:189], v[80:83]
	v_mfma_f32_16x16x32_bf16 v[68:71], v[230:233], v[222:225], v[68:71]
	v_mfma_f32_16x16x32_bf16 v[64:67], v[238:241], v[222:225], v[64:67]
	s_waitcnt lgkmcnt(0)
	v_mfma_f32_16x16x32_bf16 v[116:119], v[234:237], v[174:177], v[116:119]
	v_mfma_f32_16x16x32_bf16 v[112:115], v[242:245], v[174:177], v[112:115]
	v_mfma_f32_16x16x32_bf16 v[100:103], v[234:237], v[182:185], v[100:103]
	v_mfma_f32_16x16x32_bf16 v[96:99], v[242:245], v[182:185], v[96:99]
	v_mfma_f32_16x16x32_bf16 v[84:87], v[234:237], v[218:221], v[84:87]
	v_mfma_f32_16x16x32_bf16 v[80:83], v[242:245], v[218:221], v[80:83]
	v_mfma_f32_16x16x32_bf16 v[68:71], v[234:237], v[226:229], v[68:71]
	v_mfma_f32_16x16x32_bf16 v[64:67], v[242:245], v[226:229], v[64:67]
	s_setprio 0
	s_mov_b32 m0, s52
	v_lshl_add_u64 v[190:191], v[248:249], 0, s[66:67]
	s_barrier
	ds_read_b128 v[170:173], v216 offset:49152
	ds_read_b128 v[178:181], v216 offset:51200
	ds_read_b128 v[186:189], v216 offset:53248
	ds_read_b128 v[222:225], v216 offset:55296
	ds_read_b128 v[174:177], v216 offset:50176
	ds_read_b128 v[182:185], v216 offset:52224
	ds_read_b128 v[218:221], v216 offset:54272
	ds_read_b128 v[226:229], v216 offset:56320
	global_load_lds_dwordx4 v[190:191], off
	v_lshl_add_u64 v[190:191], v[250:251], 0, s[66:67]
	s_mov_b32 m0, s53
	s_nop 0
	global_load_lds_dwordx4 v[190:191], off
	s_waitcnt vmcnt(10)
	s_barrier
	s_waitcnt lgkmcnt(4)
	s_setprio 1
	v_mfma_f32_16x16x32_bf16 v[60:63], v[128:131], v[170:173], v[60:63]
	v_mfma_f32_16x16x32_bf16 v[56:59], v[162:165], v[170:173], v[56:59]
	v_mfma_f32_16x16x32_bf16 v[44:47], v[128:131], v[178:181], v[44:47]
	v_mfma_f32_16x16x32_bf16 v[40:43], v[162:165], v[178:181], v[40:43]
	v_mfma_f32_16x16x32_bf16 v[28:31], v[128:131], v[186:189], v[28:31]
	v_mfma_f32_16x16x32_bf16 v[24:27], v[162:165], v[186:189], v[24:27]
	v_mfma_f32_16x16x32_bf16 v[12:15], v[128:131], v[222:225], v[12:15]
	v_mfma_f32_16x16x32_bf16 v[8:11], v[162:165], v[222:225], v[8:11]
	s_waitcnt lgkmcnt(0)
	v_mfma_f32_16x16x32_bf16 v[60:63], v[158:161], v[174:177], v[60:63]
	v_mfma_f32_16x16x32_bf16 v[56:59], v[166:169], v[174:177], v[56:59]
	v_mfma_f32_16x16x32_bf16 v[44:47], v[158:161], v[182:185], v[44:47]
	v_mfma_f32_16x16x32_bf16 v[40:43], v[166:169], v[182:185], v[40:43]
	v_mfma_f32_16x16x32_bf16 v[28:31], v[158:161], v[218:221], v[28:31]
	v_mfma_f32_16x16x32_bf16 v[24:27], v[166:169], v[218:221], v[24:27]
	v_mfma_f32_16x16x32_bf16 v[12:15], v[158:161], v[226:229], v[12:15]
	v_mfma_f32_16x16x32_bf16 v[8:11], v[166:169], v[226:229], v[8:11]
	s_setprio 0
	s_barrier
	s_add_u32 s6, s6, 0x40080
	s_addc_u32 s7, s7, 0
	s_add_i32 s10, s10, s15
	s_mov_b32 m0, s10
	s_nop 0
	global_load_lds_dwordx4 v150, s[6:7]
	s_add_i32 m0, s10, 0x2000
	s_nop 0
	global_load_lds_dwordx4 v152, s[6:7]
	v_add_u32_e32 v166, 0x10000, v215
	ds_read_b128 v[128:131], v166
	ds_read_b128 v[158:161], v166 offset:1024
	ds_read_b128 v[162:165], v166 offset:2048
	ds_read_b128 v[166:169], v166 offset:3072
	s_waitcnt vmcnt(10)
	s_barrier
	s_setprio 1
	v_mfma_f32_16x16x32_bf16 v[52:55], v[230:233], v[170:173], v[52:55]
	v_mfma_f32_16x16x32_bf16 v[48:51], v[238:241], v[170:173], v[48:51]
	v_mfma_f32_16x16x32_bf16 v[36:39], v[230:233], v[178:181], v[36:39]
	v_mfma_f32_16x16x32_bf16 v[32:35], v[238:241], v[178:181], v[32:35]
	v_mfma_f32_16x16x32_bf16 v[20:23], v[230:233], v[186:189], v[20:23]
	v_mfma_f32_16x16x32_bf16 v[16:19], v[238:241], v[186:189], v[16:19]
	v_mfma_f32_16x16x32_bf16 v[4:7], v[230:233], v[222:225], v[4:7]
	v_mfma_f32_16x16x32_bf16 v[0:3], v[238:241], v[222:225], v[0:3]
	v_mfma_f32_16x16x32_bf16 v[52:55], v[234:237], v[174:177], v[52:55]
	v_mfma_f32_16x16x32_bf16 v[48:51], v[242:245], v[174:177], v[48:51]
	v_mfma_f32_16x16x32_bf16 v[36:39], v[234:237], v[182:185], v[36:39]
	v_mfma_f32_16x16x32_bf16 v[32:35], v[242:245], v[182:185], v[32:35]
	v_mfma_f32_16x16x32_bf16 v[20:23], v[234:237], v[218:221], v[20:23]
	v_mfma_f32_16x16x32_bf16 v[16:19], v[242:245], v[218:221], v[16:19]
	v_mfma_f32_16x16x32_bf16 v[4:7], v[234:237], v[226:229], v[4:7]
	v_mfma_f32_16x16x32_bf16 v[0:3], v[242:245], v[226:229], v[0:3]
	s_setprio 0
	s_add_i32 s28, s28, 2
	s_add_u32 s2, s2, 0x100
	s_addc_u32 s3, s3, 0
	s_add_u32 s19, s19, 0x100
	s_addc_u32 s27, s27, 0
	s_cmp_gt_u32 s28, 13
	s_barrier
	s_cbranch_scc0 .LBB0_145
	s_waitcnt lgkmcnt(0)
	v_mov_b32_e32 v166, v135
	s_mov_b64 s[2:3], s[0:1]
	v_readfirstlane_b32 s27, v166
	s_bfe_u32 s19, s27, 0x20006
	s_load_dwordx2 s[30:31], s[2:3], 0x88
	s_mov_b64 s[2:3], s[0:1]
	s_cmp_gt_i32 s8, 31
	s_load_dwordx2 s[28:29], s[2:3], 0x80
	s_cselect_b64 s[6:7], -1, 0
	s_cmp_lt_i32 s8, 32
	s_cselect_b64 s[2:3], -1, 0
	s_ashr_i32 s9, s27, 2
	s_lshl_b32 s8, s8, 8
	s_and_b32 s17, s9, 0xffffffc0
	v_and_b32_e32 v217, 15, v166
	s_add_i32 s17, s17, s8
	v_bfe_u32 v186, v166, 4, 2
	v_or_b32_e32 v158, s17, v217
	s_cmp_gt_i32 s26, 3
	s_mov_b64 s[8:9], -1
	s_cbranch_scc0 .LBB0_829
	s_cmp_gt_u32 s26, 5
	s_cbranch_scc0 .LBB0_409
	s_cmp_gt_u32 s26, 8
	s_cbranch_scc0 .LBB0_406
	s_waitcnt lgkmcnt(0)
	v_and_b32_e32 v128, 1, v166
	v_cmp_eq_u32_e64 s[8:9], 0, v128
	v_cmp_eq_u32_e32 vcc, 1, v128
	s_mov_b32 s10, 0x05040100
	s_mov_b32 s11, 0x07060302
	s_cmp_eq_u32 s6, 0
	s_cbranch_scc1 .Lvf_f_c

.LBB0_1104:
	s_add_u32 s22, s18, 0xfffc0080
	s_addc_u32 s23, s19, -1
	s_add_i32 s47, 0, 0x10000
	s_cmp_eq_u32 s46, 12
	s_cselect_b32 s25, s9, s23
	s_cselect_b32 s24, s42, s22
	s_cselect_b32 s23, s7, s45
	s_cselect_b32 s22, s43, s44
	s_add_i32 m0, s17, 0xc000
	ds_read_b128 v[172:175], v155
	ds_read_b128 v[180:183], v155 offset:2048
	ds_read_b128 v[188:191], v155 offset:4096
	ds_read_b128 v[220:223], v155 offset:6144
	ds_read_b128 v[176:179], v155 offset:1024
	ds_read_b128 v[184:187], v155 offset:3072
	ds_read_b128 v[216:219], v155 offset:5120
	ds_read_b128 v[224:227], v155 offset:7168
	global_load_lds_dwordx4 v130, s[18:19]
	s_add_i32 m0, s17, 0xe000
	s_nop 0
	global_load_lds_dwordx4 v150, s[18:19]
	s_waitcnt lgkmcnt(8)
	s_waitcnt vmcnt(10)
	s_barrier
	s_waitcnt lgkmcnt(4)
	s_setprio 1
	v_mfma_f32_16x16x32_bf16 v[124:127], v[156:159], v[172:175], v[124:127]
	v_mfma_f32_16x16x32_bf16 v[120:123], v[164:167], v[172:175], v[120:123]
	v_mfma_f32_16x16x32_bf16 v[108:111], v[156:159], v[180:183], v[108:111]
	v_mfma_f32_16x16x32_bf16 v[104:107], v[164:167], v[180:183], v[104:107]
	v_mfma_f32_16x16x32_bf16 v[92:95], v[156:159], v[188:191], v[92:95]
	v_mfma_f32_16x16x32_bf16 v[88:91], v[164:167], v[188:191], v[88:91]
	v_mfma_f32_16x16x32_bf16 v[76:79], v[156:159], v[220:223], v[76:79]
	v_mfma_f32_16x16x32_bf16 v[72:75], v[164:167], v[220:223], v[72:75]
	s_waitcnt lgkmcnt(0)
	v_mfma_f32_16x16x32_bf16 v[124:127], v[160:163], v[176:179], v[124:127]
	v_mfma_f32_16x16x32_bf16 v[120:123], v[168:171], v[176:179], v[120:123]
	v_mfma_f32_16x16x32_bf16 v[108:111], v[160:163], v[184:187], v[108:111]
	v_mfma_f32_16x16x32_bf16 v[104:107], v[168:171], v[184:187], v[104:107]
	v_mfma_f32_16x16x32_bf16 v[92:95], v[160:163], v[216:219], v[92:95]
	v_mfma_f32_16x16x32_bf16 v[88:91], v[168:171], v[216:219], v[88:91]
	v_mfma_f32_16x16x32_bf16 v[76:79], v[160:163], v[224:227], v[76:79]
	v_mfma_f32_16x16x32_bf16 v[72:75], v[168:171], v[224:227], v[72:75]
	s_setprio 0
	s_barrier
	s_add_i32 s50, 0, 0x14000
	v_add_u32_e32 v152, s50, v154
	s_add_i32 s47, s47, s29
	ds_read_b128 v[228:231], v152
	ds_read_b128 v[236:239], v152 offset:2048
	ds_read_b128 v[232:235], v152 offset:1024
	ds_read_b128 v[240:243], v152 offset:3072
	s_mov_b32 m0, s47
	s_nop 0
	global_load_lds_dwordx4 v132, s[22:23]
	s_add_i32 m0, s47, 0x2000
	s_nop 0
	global_load_lds_dwordx4 v128, s[22:23]
	s_waitcnt vmcnt(10)
	s_barrier
	s_waitcnt lgkmcnt(2)
	s_setprio 1
	v_mfma_f32_16x16x32_bf16 v[116:119], v[228:231], v[172:175], v[116:119]
	v_mfma_f32_16x16x32_bf16 v[112:115], v[236:239], v[172:175], v[112:115]
	v_mfma_f32_16x16x32_bf16 v[100:103], v[228:231], v[180:183], v[100:103]
	v_mfma_f32_16x16x32_bf16 v[96:99], v[236:239], v[180:183], v[96:99]
	v_mfma_f32_16x16x32_bf16 v[84:87], v[228:231], v[188:191], v[84:87]
	v_mfma_f32_16x16x32_bf16 v[80:83], v[236:239], v[188:191], v[80:83]
	v_mfma_f32_16x16x32_bf16 v[68:71], v[228:231], v[220:223], v[68:71]
	v_mfma_f32_16x16x32_bf16 v[64:67], v[236:239], v[220:223], v[64:67]
	s_waitcnt lgkmcnt(0)
	v_mfma_f32_16x16x32_bf16 v[116:119], v[232:235], v[176:179], v[116:119]
	v_mfma_f32_16x16x32_bf16 v[112:115], v[240:243], v[176:179], v[112:115]
	v_mfma_f32_16x16x32_bf16 v[100:103], v[232:235], v[184:187], v[100:103]
	v_mfma_f32_16x16x32_bf16 v[96:99], v[240:243], v[184:187], v[96:99]
	v_mfma_f32_16x16x32_bf16 v[84:87], v[232:235], v[216:219], v[84:87]
	v_mfma_f32_16x16x32_bf16 v[80:83], v[240:243], v[216:219], v[80:83]
	v_mfma_f32_16x16x32_bf16 v[68:71], v[232:235], v[224:227], v[68:71]
	v_mfma_f32_16x16x32_bf16 v[64:67], v[240:243], v[224:227], v[64:67]
	s_setprio 0
	s_mov_b32 m0, s17
	v_lshl_add_u64 v[246:247], s[24:25], 0, v[132:133]
	s_barrier
	ds_read_b128 v[172:175], v155 offset:16384
	ds_read_b128 v[180:183], v155 offset:18432
	ds_read_b128 v[188:191], v155 offset:20480
	ds_read_b128 v[220:223], v155 offset:22528
	ds_read_b128 v[176:179], v155 offset:17408
	ds_read_b128 v[184:187], v155 offset:19456
	ds_read_b128 v[216:219], v155 offset:21504
	ds_read_b128 v[224:227], v155 offset:23552
	global_load_lds_dwordx4 v132, s[24:25]
	v_lshl_add_u64 v[248:249], s[24:25], 0, v[128:129]
	s_mov_b32 m0, s31
	s_nop 0
	global_load_lds_dwordx4 v128, s[24:25]
	s_waitcnt vmcnt(10)
	s_barrier
	s_waitcnt lgkmcnt(4)
	s_setprio 1
	v_mfma_f32_16x16x32_bf16 v[60:63], v[156:159], v[172:175], v[60:63]
	v_mfma_f32_16x16x32_bf16 v[56:59], v[164:167], v[172:175], v[56:59]
	v_mfma_f32_16x16x32_bf16 v[44:47], v[156:159], v[180:183], v[44:47]
	v_mfma_f32_16x16x32_bf16 v[40:43], v[164:167], v[180:183], v[40:43]
	v_mfma_f32_16x16x32_bf16 v[28:31], v[156:159], v[188:191], v[28:31]
	v_mfma_f32_16x16x32_bf16 v[24:27], v[164:167], v[188:191], v[24:27]
	v_mfma_f32_16x16x32_bf16 v[12:15], v[156:159], v[220:223], v[12:15]
	v_mfma_f32_16x16x32_bf16 v[8:11], v[164:167], v[220:223], v[8:11]
	s_waitcnt lgkmcnt(0)
	v_mfma_f32_16x16x32_bf16 v[60:63], v[160:163], v[176:179], v[60:63]
	v_mfma_f32_16x16x32_bf16 v[56:59], v[168:171], v[176:179], v[56:59]
	v_mfma_f32_16x16x32_bf16 v[44:47], v[160:163], v[184:187], v[44:47]
	v_mfma_f32_16x16x32_bf16 v[40:43], v[168:171], v[184:187], v[40:43]
	v_mfma_f32_16x16x32_bf16 v[28:31], v[160:163], v[216:219], v[28:31]
	v_mfma_f32_16x16x32_bf16 v[24:27], v[168:171], v[216:219], v[24:27]
	v_mfma_f32_16x16x32_bf16 v[12:15], v[160:163], v[224:227], v[12:15]
	v_mfma_f32_16x16x32_bf16 v[8:11], v[168:171], v[224:227], v[8:11]
	s_setprio 0
	s_barrier
	s_add_u32 s48, s22, 0x40000
	s_addc_u32 s49, s23, 0
	s_add_i32 s47, s50, s29
	s_mov_b32 m0, s47
	s_nop 0
	global_load_lds_dwordx4 v132, s[48:49]
	s_add_i32 m0, s47, 0x2000
	s_nop 0
	global_load_lds_dwordx4 v128, s[48:49]
	v_add_u32_e32 v168, 0x18000, v154
	ds_read_b128 v[156:159], v168
	ds_read_b128 v[160:163], v168 offset:1024
	ds_read_b128 v[164:167], v168 offset:2048
	ds_read_b128 v[168:171], v168 offset:3072
	s_waitcnt vmcnt(10)
	s_barrier
	s_setprio 1
	v_mfma_f32_16x16x32_bf16 v[52:55], v[228:231], v[172:175], v[52:55]
	v_mfma_f32_16x16x32_bf16 v[48:51], v[236:239], v[172:175], v[48:51]
	v_mfma_f32_16x16x32_bf16 v[36:39], v[228:231], v[180:183], v[36:39]
	v_mfma_f32_16x16x32_bf16 v[32:35], v[236:239], v[180:183], v[32:35]
	v_mfma_f32_16x16x32_bf16 v[20:23], v[228:231], v[188:191], v[20:23]
	v_mfma_f32_16x16x32_bf16 v[16:19], v[236:239], v[188:191], v[16:19]
	v_mfma_f32_16x16x32_bf16 v[4:7], v[228:231], v[220:223], v[4:7]
	v_mfma_f32_16x16x32_bf16 v[0:3], v[236:239], v[220:223], v[0:3]
	v_mfma_f32_16x16x32_bf16 v[52:55], v[232:235], v[176:179], v[52:55]
	v_mfma_f32_16x16x32_bf16 v[48:51], v[240:243], v[176:179], v[48:51]
	v_mfma_f32_16x16x32_bf16 v[36:39], v[232:235], v[184:187], v[36:39]
	v_mfma_f32_16x16x32_bf16 v[32:35], v[240:243], v[184:187], v[32:35]
	v_mfma_f32_16x16x32_bf16 v[20:23], v[232:235], v[216:219], v[20:23]
	v_mfma_f32_16x16x32_bf16 v[16:19], v[240:243], v[216:219], v[16:19]
	v_mfma_f32_16x16x32_bf16 v[4:7], v[232:235], v[224:227], v[4:7]
	v_mfma_f32_16x16x32_bf16 v[0:3], v[240:243], v[224:227], v[0:3]
	s_setprio 0
	s_add_i32 s47, 0, 0x18000
	s_barrier
	s_add_u32 s24, s24, 0x40000
	s_addc_u32 s25, s25, 0
	s_mov_b32 m0, s34
	ds_read_b128 v[172:175], v155 offset:32768
	ds_read_b128 v[180:183], v155 offset:34816
	ds_read_b128 v[188:191], v155 offset:36864
	ds_read_b128 v[220:223], v155 offset:38912
	ds_read_b128 v[176:179], v155 offset:33792
	ds_read_b128 v[184:187], v155 offset:35840
	ds_read_b128 v[216:219], v155 offset:37888
	ds_read_b128 v[224:227], v155 offset:39936
	global_load_lds_dwordx4 v132, s[24:25]
	s_mov_b32 m0, s35
	s_nop 0
	global_load_lds_dwordx4 v128, s[24:25]
	s_waitcnt lgkmcnt(8)
	s_waitcnt vmcnt(10)
	s_barrier
	s_waitcnt lgkmcnt(4)
	s_setprio 1
	v_mfma_f32_16x16x32_bf16 v[124:127], v[156:159], v[172:175], v[124:127]
	v_mfma_f32_16x16x32_bf16 v[120:123], v[164:167], v[172:175], v[120:123]
	v_mfma_f32_16x16x32_bf16 v[108:111], v[156:159], v[180:183], v[108:111]
	v_mfma_f32_16x16x32_bf16 v[104:107], v[164:167], v[180:183], v[104:107]
	v_mfma_f32_16x16x32_bf16 v[92:95], v[156:159], v[188:191], v[92:95]
	v_mfma_f32_16x16x32_bf16 v[88:91], v[164:167], v[188:191], v[88:91]
	v_mfma_f32_16x16x32_bf16 v[76:79], v[156:159], v[220:223], v[76:79]
	v_mfma_f32_16x16x32_bf16 v[72:75], v[164:167], v[220:223], v[72:75]
	s_waitcnt lgkmcnt(0)
	v_mfma_f32_16x16x32_bf16 v[124:127], v[160:163], v[176:179], v[124:127]
	v_mfma_f32_16x16x32_bf16 v[120:123], v[168:171], v[176:179], v[120:123]
	v_mfma_f32_16x16x32_bf16 v[108:111], v[160:163], v[184:187], v[108:111]
	v_mfma_f32_16x16x32_bf16 v[104:107], v[168:171], v[184:187], v[104:107]
	v_mfma_f32_16x16x32_bf16 v[92:95], v[160:163], v[216:219], v[92:95]
	v_mfma_f32_16x16x32_bf16 v[88:91], v[168:171], v[216:219], v[88:91]
	v_mfma_f32_16x16x32_bf16 v[76:79], v[160:163], v[224:227], v[76:79]
	v_mfma_f32_16x16x32_bf16 v[72:75], v[168:171], v[224:227], v[72:75]
	s_setprio 0
	s_barrier
	s_add_i32 s24, 0, 0x1c000
	s_add_i32 s25, s47, s29
	v_add_u32_e32 v200, s24, v154
	s_mov_b32 m0, s25
	ds_read_b128 v[228:231], v200
	ds_read_b128 v[236:239], v200 offset:2048
	ds_read_b128 v[232:235], v200 offset:1024
	ds_read_b128 v[240:243], v200 offset:3072
	s_add_u32 s98, s22, 0x80
	s_addc_u32 s99, s23, 0
	global_load_lds_dwordx4 v132, s[98:99]
	s_add_i32 m0, s25, 0x2000
	s_nop 0
	global_load_lds_dwordx4 v128, s[98:99]
	s_waitcnt vmcnt(10)
	s_barrier
	s_waitcnt lgkmcnt(2)
	s_setprio 1
	v_mfma_f32_16x16x32_bf16 v[116:119], v[228:231], v[172:175], v[116:119]
	v_mfma_f32_16x16x32_bf16 v[112:115], v[236:239], v[172:175], v[112:115]
	v_mfma_f32_16x16x32_bf16 v[100:103], v[228:231], v[180:183], v[100:103]
	v_mfma_f32_16x16x32_bf16 v[96:99], v[236:239], v[180:183], v[96:99]
	v_mfma_f32_16x16x32_bf16 v[84:87], v[228:231], v[188:191], v[84:87]
	v_mfma_f32_16x16x32_bf16 v[80:83], v[236:239], v[188:191], v[80:83]
	v_mfma_f32_16x16x32_bf16 v[68:71], v[228:231], v[220:223], v[68:71]
	v_mfma_f32_16x16x32_bf16 v[64:67], v[236:239], v[220:223], v[64:67]
	s_waitcnt lgkmcnt(0)
	v_mfma_f32_16x16x32_bf16 v[116:119], v[232:235], v[176:179], v[116:119]
	v_mfma_f32_16x16x32_bf16 v[112:115], v[240:243], v[176:179], v[112:115]
	v_mfma_f32_16x16x32_bf16 v[100:103], v[232:235], v[184:187], v[100:103]
	v_mfma_f32_16x16x32_bf16 v[96:99], v[240:243], v[184:187], v[96:99]
	v_mfma_f32_16x16x32_bf16 v[84:87], v[232:235], v[216:219], v[84:87]
	v_mfma_f32_16x16x32_bf16 v[80:83], v[240:243], v[216:219], v[80:83]
	v_mfma_f32_16x16x32_bf16 v[68:71], v[232:235], v[224:227], v[68:71]
	v_mfma_f32_16x16x32_bf16 v[64:67], v[240:243], v[224:227], v[64:67]
	s_setprio 0
	s_mov_b32 m0, s36
	v_lshl_add_u64 v[152:153], v[246:247], 0, s[66:67]
	s_barrier
	ds_read_b128 v[172:175], v155 offset:49152
	ds_read_b128 v[180:183], v155 offset:51200
	ds_read_b128 v[188:191], v155 offset:53248
	ds_read_b128 v[220:223], v155 offset:55296
	ds_read_b128 v[176:179], v155 offset:50176
	ds_read_b128 v[184:187], v155 offset:52224
	ds_read_b128 v[216:219], v155 offset:54272
	ds_read_b128 v[224:227], v155 offset:56320
	global_load_lds_dwordx4 v[152:153], off
	v_lshl_add_u64 v[152:153], v[248:249], 0, s[66:67]
	s_mov_b32 m0, s37
	s_nop 0
	global_load_lds_dwordx4 v[152:153], off
	s_waitcnt vmcnt(10)
	s_barrier
	s_waitcnt lgkmcnt(4)
	s_setprio 1
	v_mfma_f32_16x16x32_bf16 v[60:63], v[156:159], v[172:175], v[60:63]
	v_mfma_f32_16x16x32_bf16 v[56:59], v[164:167], v[172:175], v[56:59]
	v_mfma_f32_16x16x32_bf16 v[44:47], v[156:159], v[180:183], v[44:47]
	v_mfma_f32_16x16x32_bf16 v[40:43], v[164:167], v[180:183], v[40:43]
	v_mfma_f32_16x16x32_bf16 v[28:31], v[156:159], v[188:191], v[28:31]
	v_mfma_f32_16x16x32_bf16 v[24:27], v[164:167], v[188:191], v[24:27]
	v_mfma_f32_16x16x32_bf16 v[12:15], v[156:159], v[220:223], v[12:15]
	v_mfma_f32_16x16x32_bf16 v[8:11], v[164:167], v[220:223], v[8:11]
	s_waitcnt lgkmcnt(0)
	v_mfma_f32_16x16x32_bf16 v[60:63], v[160:163], v[176:179], v[60:63]
	v_mfma_f32_16x16x32_bf16 v[56:59], v[168:171], v[176:179], v[56:59]
	v_mfma_f32_16x16x32_bf16 v[44:47], v[160:163], v[184:187], v[44:47]
	v_mfma_f32_16x16x32_bf16 v[40:43], v[168:171], v[184:187], v[40:43]
	v_mfma_f32_16x16x32_bf16 v[28:31], v[160:163], v[216:219], v[28:31]
	v_mfma_f32_16x16x32_bf16 v[24:27], v[168:171], v[216:219], v[24:27]
	v_mfma_f32_16x16x32_bf16 v[12:15], v[160:163], v[224:227], v[12:15]
	v_mfma_f32_16x16x32_bf16 v[8:11], v[168:171], v[224:227], v[8:11]
	s_setprio 0
	s_barrier
	s_add_u32 s22, s22, 0x40080
	s_addc_u32 s23, s23, 0
	s_add_i32 s24, s24, s29
	s_mov_b32 m0, s24
	s_nop 0
	global_load_lds_dwordx4 v132, s[22:23]
	s_add_i32 m0, s24, 0x2000
	s_nop 0
	global_load_lds_dwordx4 v128, s[22:23]
	v_add_u32_e32 v168, 0x10000, v154
	ds_read_b128 v[156:159], v168
	ds_read_b128 v[160:163], v168 offset:1024
	ds_read_b128 v[164:167], v168 offset:2048
	ds_read_b128 v[168:171], v168 offset:3072
	s_waitcnt vmcnt(10)
	s_barrier
	s_setprio 1
	v_mfma_f32_16x16x32_bf16 v[52:55], v[228:231], v[172:175], v[52:55]
	v_mfma_f32_16x16x32_bf16 v[48:51], v[236:239], v[172:175], v[48:51]
	v_mfma_f32_16x16x32_bf16 v[36:39], v[228:231], v[180:183], v[36:39]
	v_mfma_f32_16x16x32_bf16 v[32:35], v[236:239], v[180:183], v[32:35]
	v_mfma_f32_16x16x32_bf16 v[20:23], v[228:231], v[188:191], v[20:23]
	v_mfma_f32_16x16x32_bf16 v[16:19], v[236:239], v[188:191], v[16:19]
	v_mfma_f32_16x16x32_bf16 v[4:7], v[228:231], v[220:223], v[4:7]
	v_mfma_f32_16x16x32_bf16 v[0:3], v[236:239], v[220:223], v[0:3]
	v_mfma_f32_16x16x32_bf16 v[52:55], v[232:235], v[176:179], v[52:55]
	v_mfma_f32_16x16x32_bf16 v[48:51], v[240:243], v[176:179], v[48:51]
	v_mfma_f32_16x16x32_bf16 v[36:39], v[232:235], v[184:187], v[36:39]
	v_mfma_f32_16x16x32_bf16 v[32:35], v[240:243], v[184:187], v[32:35]
	v_mfma_f32_16x16x32_bf16 v[20:23], v[232:235], v[216:219], v[20:23]
	v_mfma_f32_16x16x32_bf16 v[16:19], v[240:243], v[216:219], v[16:19]
	v_mfma_f32_16x16x32_bf16 v[4:7], v[232:235], v[224:227], v[4:7]
	v_mfma_f32_16x16x32_bf16 v[0:3], v[240:243], v[224:227], v[0:3]
	s_setprio 0
	s_add_i32 s46, s46, 2
	s_add_u32 s18, s18, 0x100
	s_addc_u32 s19, s19, 0
	s_add_u32 s44, s44, 0x100
	s_addc_u32 s45, s45, 0
	s_cmp_gt_u32 s46, 13
	s_barrier
	s_cbranch_scc0 .LBB0_1104
	s_waitcnt lgkmcnt(0)
	v_mov_b32_e32 v153, v135
	s_mov_b64 s[18:19], s[0:1]
	s_load_dwordx2 s[18:19], s[18:19], 0x88
	s_nop 0
	v_readfirstlane_b32 s7, v153
	s_ashr_i32 s9, s7, 2
	s_lshr_b32 s7, s7, 1
	s_lshl_b32 s22, s41, 7
	s_and_b32 s7, s7, 0x60
	s_andn2_b32 s9, s9, 63
	s_or_b32 s7, s7, s22
	v_lshrrev_b32_e32 v152, 1, v153
	v_and_or_b32 v152, v152, 24, s7
	v_and_or_b32 v153, v153, 15, s9
	v_lshl_add_u32 v156, s16, 8, v153
	v_ashrrev_i32_e32 v153, 31, v152
	v_mov_b32_e32 v168, 0xbfb8aa3b
	v_mov_b32_e32 v169, 0xbfb8aa3b
	v_mov_b32_e32 v170, 1.0
	v_mov_b32_e32 v171, 1.0
	v_pk_mul_f32 v[160:161], v[124:125], v[168:169]
	v_pk_mul_f32 v[162:163], v[126:127], v[168:169]
	v_pk_mul_f32 v[164:165], v[116:117], v[168:169]
	v_pk_mul_f32 v[166:167], v[118:119], v[168:169]
	v_exp_f32_e32 v160, v160
	v_exp_f32_e32 v161, v161
	v_exp_f32_e32 v162, v162
	v_exp_f32_e32 v163, v163
	v_exp_f32_e32 v164, v164
	v_exp_f32_e32 v165, v165
	v_exp_f32_e32 v166, v166
	v_exp_f32_e32 v167, v167
	s_waitcnt lgkmcnt(0)
	v_lshl_add_u64 v[152:153], v[152:153], 1, s[18:19]
	s_mov_b64 s[18:19], 0xa2a4400
	v_lshl_add_u64 v[152:153], v[152:153], 0, s[18:19]
	s_and_b64 vcc, exec, s[4:5]
	s_mov_b32 s41, s6
	s_mov_b32 s16, s8
	s_mov_b64 s[22:23], s[12:13]
	v_pk_add_f32 v[160:161], v[160:161], v[170:171]
	v_pk_add_f32 v[162:163], v[162:163], v[170:171]
	v_pk_add_f32 v[164:165], v[164:165], v[170:171]
	v_pk_add_f32 v[166:167], v[166:167], v[170:171]
	v_rcp_f32_e32 v160, v160
	v_rcp_f32_e32 v161, v161
	v_rcp_f32_e32 v162, v162
	v_rcp_f32_e32 v163, v163
	v_rcp_f32_e32 v164, v164
	v_rcp_f32_e32 v165, v165
	v_rcp_f32_e32 v166, v166
	v_rcp_f32_e32 v167, v167
	v_mov_b32_e32 v158, v156
	v_mad_i64_i32 v[158:159], s[18:19], v158, s73, v[152:153]
	v_pk_mul_f32 v[124:125], v[124:125], v[160:161]
	v_pk_mul_f32 v[126:127], v[126:127], v[162:163]
	v_pk_mul_f32 v[116:117], v[116:117], v[164:165]
	v_pk_mul_f32 v[118:119], v[118:119], v[166:167]
	v_pk_mul_f32 v[120:121], v[120:121], v[124:125]
	v_pk_mul_f32 v[122:123], v[122:123], v[126:127]
	v_pk_mul_f32 v[112:113], v[112:113], v[116:117]
	v_pk_mul_f32 v[114:115], v[114:115], v[118:119]
	v_cvt_pk_bf16_f32 v120, v120, v121
	v_cvt_pk_bf16_f32 v121, v122, v123
	v_cvt_pk_bf16_f32 v122, v112, v113
	v_cvt_pk_bf16_f32 v123, v114, v115
	global_store_dwordx4 v[158:159], v[120:123], off sc1
	v_pk_mul_f32 v[160:161], v[108:109], v[168:169]
	v_pk_mul_f32 v[162:163], v[110:111], v[168:169]
	v_pk_mul_f32 v[164:165], v[100:101], v[168:169]
	v_pk_mul_f32 v[166:167], v[102:103], v[168:169]
	v_exp_f32_e32 v160, v160
	v_exp_f32_e32 v161, v161
	v_exp_f32_e32 v162, v162
	v_exp_f32_e32 v163, v163
	v_exp_f32_e32 v164, v164
	v_exp_f32_e32 v165, v165
	v_exp_f32_e32 v166, v166
	v_exp_f32_e32 v167, v167
	v_pk_add_f32 v[160:161], v[160:161], v[170:171]
	v_pk_add_f32 v[162:163], v[162:163], v[170:171]
	v_pk_add_f32 v[164:165], v[164:165], v[170:171]
	v_pk_add_f32 v[166:167], v[166:167], v[170:171]
	v_rcp_f32_e32 v160, v160
	v_rcp_f32_e32 v161, v161
	v_rcp_f32_e32 v162, v162
	v_rcp_f32_e32 v163, v163
	v_rcp_f32_e32 v164, v164
	v_rcp_f32_e32 v165, v165
	v_rcp_f32_e32 v166, v166
	v_rcp_f32_e32 v167, v167
	v_add_u32_e32 v158, 0x10, v156
	v_mad_i64_i32 v[158:159], s[18:19], v158, s73, v[152:153]
	v_pk_mul_f32 v[108:109], v[108:109], v[160:161]
	v_pk_mul_f32 v[110:111], v[110:111], v[162:163]
	v_pk_mul_f32 v[100:101], v[100:101], v[164:165]
	v_pk_mul_f32 v[102:103], v[102:103], v[166:167]
	v_pk_mul_f32 v[104:105], v[104:105], v[108:109]
	v_pk_mul_f32 v[106:107], v[106:107], v[110:111]
	v_pk_mul_f32 v[96:97], v[96:97], v[100:101]
	v_pk_mul_f32 v[98:99], v[98:99], v[102:103]
	v_cvt_pk_bf16_f32 v104, v104, v105
	v_cvt_pk_bf16_f32 v105, v106, v107
	v_cvt_pk_bf16_f32 v106, v96, v97
	v_cvt_pk_bf16_f32 v107, v98, v99
	global_store_dwordx4 v[158:159], v[104:107], off sc1
	v_pk_mul_f32 v[160:161], v[92:93], v[168:169]
	v_pk_mul_f32 v[162:163], v[94:95], v[168:169]
	v_pk_mul_f32 v[164:165], v[84:85], v[168:169]
	v_pk_mul_f32 v[166:167], v[86:87], v[168:169]
	v_exp_f32_e32 v160, v160
	v_exp_f32_e32 v161, v161
	v_exp_f32_e32 v162, v162
	v_exp_f32_e32 v163, v163
	v_exp_f32_e32 v164, v164
	v_exp_f32_e32 v165, v165
	v_exp_f32_e32 v166, v166
	v_exp_f32_e32 v167, v167
	v_pk_add_f32 v[160:161], v[160:161], v[170:171]
	v_pk_add_f32 v[162:163], v[162:163], v[170:171]
	v_pk_add_f32 v[164:165], v[164:165], v[170:171]
	v_pk_add_f32 v[166:167], v[166:167], v[170:171]
	v_rcp_f32_e32 v160, v160
	v_rcp_f32_e32 v161, v161
	v_rcp_f32_e32 v162, v162
	v_rcp_f32_e32 v163, v163
	v_rcp_f32_e32 v164, v164
	v_rcp_f32_e32 v165, v165
	v_rcp_f32_e32 v166, v166
	v_rcp_f32_e32 v167, v167
	v_add_u32_e32 v158, 0x20, v156
	v_mad_i64_i32 v[158:159], s[18:19], v158, s73, v[152:153]
	v_pk_mul_f32 v[92:93], v[92:93], v[160:161]
	v_pk_mul_f32 v[94:95], v[94:95], v[162:163]
	v_pk_mul_f32 v[84:85], v[84:85], v[164:165]
	v_pk_mul_f32 v[86:87], v[86:87], v[166:167]
	v_pk_mul_f32 v[88:89], v[88:89], v[92:93]
	v_pk_mul_f32 v[90:91], v[90:91], v[94:95]
	v_pk_mul_f32 v[80:81], v[80:81], v[84:85]
	v_pk_mul_f32 v[82:83], v[82:83], v[86:87]
	v_cvt_pk_bf16_f32 v88, v88, v89
	v_cvt_pk_bf16_f32 v89, v90, v91
	v_cvt_pk_bf16_f32 v90, v80, v81
	v_cvt_pk_bf16_f32 v91, v82, v83
	global_store_dwordx4 v[158:159], v[88:91], off sc1
	v_pk_mul_f32 v[160:161], v[76:77], v[168:169]
	v_pk_mul_f32 v[162:163], v[78:79], v[168:169]
	v_pk_mul_f32 v[164:165], v[68:69], v[168:169]
	v_pk_mul_f32 v[166:167], v[70:71], v[168:169]
	v_exp_f32_e32 v160, v160
	v_exp_f32_e32 v161, v161
	v_exp_f32_e32 v162, v162
	v_exp_f32_e32 v163, v163
	v_exp_f32_e32 v164, v164
	v_exp_f32_e32 v165, v165
	v_exp_f32_e32 v166, v166
	v_exp_f32_e32 v167, v167
	v_pk_add_f32 v[160:161], v[160:161], v[170:171]
	v_pk_add_f32 v[162:163], v[162:163], v[170:171]
	v_pk_add_f32 v[164:165], v[164:165], v[170:171]
	v_pk_add_f32 v[166:167], v[166:167], v[170:171]
	v_rcp_f32_e32 v160, v160
	v_rcp_f32_e32 v161, v161
	v_rcp_f32_e32 v162, v162
	v_rcp_f32_e32 v163, v163
	v_rcp_f32_e32 v164, v164
	v_rcp_f32_e32 v165, v165
	v_rcp_f32_e32 v166, v166
	v_rcp_f32_e32 v167, v167
	v_add_u32_e32 v158, 0x30, v156
	v_mad_i64_i32 v[158:159], s[18:19], v158, s73, v[152:153]
	v_pk_mul_f32 v[76:77], v[76:77], v[160:161]
	v_pk_mul_f32 v[78:79], v[78:79], v[162:163]
	v_pk_mul_f32 v[68:69], v[68:69], v[164:165]
	v_pk_mul_f32 v[70:71], v[70:71], v[166:167]
	v_pk_mul_f32 v[72:73], v[72:73], v[76:77]
	v_pk_mul_f32 v[74:75], v[74:75], v[78:79]
	v_pk_mul_f32 v[64:65], v[64:65], v[68:69]
	v_pk_mul_f32 v[66:67], v[66:67], v[70:71]
	v_cvt_pk_bf16_f32 v72, v72, v73
	v_cvt_pk_bf16_f32 v73, v74, v75
	v_cvt_pk_bf16_f32 v74, v64, v65
	v_cvt_pk_bf16_f32 v75, v66, v67
	global_store_dwordx4 v[158:159], v[72:75], off sc1
	v_pk_mul_f32 v[160:161], v[60:61], v[168:169]
	v_pk_mul_f32 v[162:163], v[62:63], v[168:169]
	v_pk_mul_f32 v[164:165], v[52:53], v[168:169]
	v_pk_mul_f32 v[166:167], v[54:55], v[168:169]
	v_exp_f32_e32 v160, v160
	v_exp_f32_e32 v161, v161
	v_exp_f32_e32 v162, v162
	v_exp_f32_e32 v163, v163
	v_exp_f32_e32 v164, v164
	v_exp_f32_e32 v165, v165
	v_exp_f32_e32 v166, v166
	v_exp_f32_e32 v167, v167
	v_pk_add_f32 v[160:161], v[160:161], v[170:171]
	v_pk_add_f32 v[162:163], v[162:163], v[170:171]
	v_pk_add_f32 v[164:165], v[164:165], v[170:171]
	v_pk_add_f32 v[166:167], v[166:167], v[170:171]
	v_rcp_f32_e32 v160, v160
	v_rcp_f32_e32 v161, v161
	v_rcp_f32_e32 v162, v162
	v_rcp_f32_e32 v163, v163
	v_rcp_f32_e32 v164, v164
	v_rcp_f32_e32 v165, v165
	v_rcp_f32_e32 v166, v166
	v_rcp_f32_e32 v167, v167
	v_add_u32_e32 v158, 0x80, v156
	v_mad_i64_i32 v[158:159], s[18:19], v158, s73, v[152:153]
	v_pk_mul_f32 v[60:61], v[60:61], v[160:161]
	v_pk_mul_f32 v[62:63], v[62:63], v[162:163]
	v_pk_mul_f32 v[52:53], v[52:53], v[164:165]
	v_pk_mul_f32 v[54:55], v[54:55], v[166:167]
	v_pk_mul_f32 v[56:57], v[56:57], v[60:61]
	v_pk_mul_f32 v[58:59], v[58:59], v[62:63]
	v_pk_mul_f32 v[48:49], v[48:49], v[52:53]
	v_pk_mul_f32 v[50:51], v[50:51], v[54:55]
	v_cvt_pk_bf16_f32 v56, v56, v57
	v_cvt_pk_bf16_f32 v57, v58, v59
	v_cvt_pk_bf16_f32 v58, v48, v49
	v_cvt_pk_bf16_f32 v59, v50, v51
	global_store_dwordx4 v[158:159], v[56:59], off sc1
	v_pk_mul_f32 v[160:161], v[44:45], v[168:169]
	v_pk_mul_f32 v[162:163], v[46:47], v[168:169]
	v_pk_mul_f32 v[164:165], v[36:37], v[168:169]
	v_pk_mul_f32 v[166:167], v[38:39], v[168:169]
	v_exp_f32_e32 v160, v160
	v_exp_f32_e32 v161, v161
	v_exp_f32_e32 v162, v162
	v_exp_f32_e32 v163, v163
	v_exp_f32_e32 v164, v164
	v_exp_f32_e32 v165, v165
	v_exp_f32_e32 v166, v166
	v_exp_f32_e32 v167, v167
	v_pk_add_f32 v[160:161], v[160:161], v[170:171]
	v_pk_add_f32 v[162:163], v[162:163], v[170:171]
	v_pk_add_f32 v[164:165], v[164:165], v[170:171]
	v_pk_add_f32 v[166:167], v[166:167], v[170:171]
	v_rcp_f32_e32 v160, v160
	v_rcp_f32_e32 v161, v161
	v_rcp_f32_e32 v162, v162
	v_rcp_f32_e32 v163, v163
	v_rcp_f32_e32 v164, v164
	v_rcp_f32_e32 v165, v165
	v_rcp_f32_e32 v166, v166
	v_rcp_f32_e32 v167, v167
	v_add_u32_e32 v158, 0x90, v156
	v_mad_i64_i32 v[158:159], s[18:19], v158, s73, v[152:153]
	v_pk_mul_f32 v[44:45], v[44:45], v[160:161]
	v_pk_mul_f32 v[46:47], v[46:47], v[162:163]
	v_pk_mul_f32 v[36:37], v[36:37], v[164:165]
	v_pk_mul_f32 v[38:39], v[38:39], v[166:167]
	v_pk_mul_f32 v[40:41], v[40:41], v[44:45]
	v_pk_mul_f32 v[42:43], v[42:43], v[46:47]
	v_pk_mul_f32 v[32:33], v[32:33], v[36:37]
	v_pk_mul_f32 v[34:35], v[34:35], v[38:39]
	v_cvt_pk_bf16_f32 v40, v40, v41
	v_cvt_pk_bf16_f32 v41, v42, v43
	v_cvt_pk_bf16_f32 v42, v32, v33
	v_cvt_pk_bf16_f32 v43, v34, v35
	global_store_dwordx4 v[158:159], v[40:43], off sc1
	v_pk_mul_f32 v[160:161], v[28:29], v[168:169]
	v_pk_mul_f32 v[162:163], v[30:31], v[168:169]
	v_pk_mul_f32 v[164:165], v[20:21], v[168:169]
	v_pk_mul_f32 v[166:167], v[22:23], v[168:169]
	v_exp_f32_e32 v160, v160
	v_exp_f32_e32 v161, v161
	v_exp_f32_e32 v162, v162
	v_exp_f32_e32 v163, v163
	v_exp_f32_e32 v164, v164
	v_exp_f32_e32 v165, v165
	v_exp_f32_e32 v166, v166
	v_exp_f32_e32 v167, v167
	v_pk_add_f32 v[160:161], v[160:161], v[170:171]
	v_pk_add_f32 v[162:163], v[162:163], v[170:171]
	v_pk_add_f32 v[164:165], v[164:165], v[170:171]
	v_pk_add_f32 v[166:167], v[166:167], v[170:171]
	v_rcp_f32_e32 v160, v160
	v_rcp_f32_e32 v161, v161
	v_rcp_f32_e32 v162, v162
	v_rcp_f32_e32 v163, v163
	v_rcp_f32_e32 v164, v164
	v_rcp_f32_e32 v165, v165
	v_rcp_f32_e32 v166, v166
	v_rcp_f32_e32 v167, v167
	v_add_u32_e32 v158, 0xa0, v156
	v_mad_i64_i32 v[158:159], s[18:19], v158, s73, v[152:153]
	v_pk_mul_f32 v[28:29], v[28:29], v[160:161]
	v_pk_mul_f32 v[30:31], v[30:31], v[162:163]
	v_pk_mul_f32 v[20:21], v[20:21], v[164:165]
	v_pk_mul_f32 v[22:23], v[22:23], v[166:167]
	v_pk_mul_f32 v[24:25], v[24:25], v[28:29]
	v_pk_mul_f32 v[26:27], v[26:27], v[30:31]
	v_pk_mul_f32 v[16:17], v[16:17], v[20:21]
	v_pk_mul_f32 v[18:19], v[18:19], v[22:23]
	v_cvt_pk_bf16_f32 v24, v24, v25
	v_cvt_pk_bf16_f32 v25, v26, v27
	v_cvt_pk_bf16_f32 v26, v16, v17
	v_cvt_pk_bf16_f32 v27, v18, v19
	global_store_dwordx4 v[158:159], v[24:27], off sc1
	v_pk_mul_f32 v[160:161], v[12:13], v[168:169]
	v_pk_mul_f32 v[162:163], v[14:15], v[168:169]
	v_pk_mul_f32 v[164:165], v[4:5], v[168:169]
	v_pk_mul_f32 v[166:167], v[6:7], v[168:169]
	v_exp_f32_e32 v160, v160
	v_exp_f32_e32 v161, v161
	v_exp_f32_e32 v162, v162
	v_exp_f32_e32 v163, v163
	v_exp_f32_e32 v164, v164
	v_exp_f32_e32 v165, v165
	v_exp_f32_e32 v166, v166
	v_exp_f32_e32 v167, v167
	v_pk_add_f32 v[160:161], v[160:161], v[170:171]
	v_pk_add_f32 v[162:163], v[162:163], v[170:171]
	v_pk_add_f32 v[164:165], v[164:165], v[170:171]
	v_pk_add_f32 v[166:167], v[166:167], v[170:171]
	v_rcp_f32_e32 v160, v160
	v_rcp_f32_e32 v161, v161
	v_rcp_f32_e32 v162, v162
	v_rcp_f32_e32 v163, v163
	v_rcp_f32_e32 v164, v164
	v_rcp_f32_e32 v165, v165
	v_rcp_f32_e32 v166, v166
	v_rcp_f32_e32 v167, v167
	v_add_u32_e32 v158, 0xb0, v156
	v_mad_i64_i32 v[158:159], s[18:19], v158, s73, v[152:153]
	v_pk_mul_f32 v[12:13], v[12:13], v[160:161]
	v_pk_mul_f32 v[14:15], v[14:15], v[162:163]
	v_pk_mul_f32 v[4:5], v[4:5], v[164:165]
	v_pk_mul_f32 v[6:7], v[6:7], v[166:167]
	v_pk_mul_f32 v[8:9], v[8:9], v[12:13]
	v_pk_mul_f32 v[10:11], v[10:11], v[14:15]
	v_pk_mul_f32 v[0:1], v[0:1], v[4:5]
	v_pk_mul_f32 v[2:3], v[2:3], v[6:7]
	v_cvt_pk_bf16_f32 v8, v8, v9
	v_cvt_pk_bf16_f32 v9, v10, v11
	v_cvt_pk_bf16_f32 v10, v0, v1
	v_cvt_pk_bf16_f32 v11, v2, v3
	global_store_dwordx4 v[158:159], v[8:11], off sc1
	s_mov_b64 s[18:19], s[10:11]
	s_cbranch_vccz .LBB0_1101
	s_waitcnt vmcnt(0)
	s_cmpk_gt_u32 s14, 0xff
	s_cbranch_scc1 .LBB0_1108
	s_barrier

.LBB0_1234:
	s_add_i32 s40, s10, 2
	s_add_u32 s12, s8, 0x80
	s_addc_u32 s11, s9, 0
	s_add_i32 s41, 0, 0x10000
	s_cmp_eq_u32 s29, s10
	s_cselect_b32 s10, s2, s12
	s_cselect_b32 s11, s3, s11
	s_cselect_b32 s13, s7, s39
	s_cselect_b32 s12, s6, s38
	s_add_i32 m0, s22, 0xc000
	ds_read_b128 v[172:175], v155
	ds_read_b128 v[180:183], v155 offset:2048
	ds_read_b128 v[188:191], v155 offset:4096
	ds_read_b128 v[220:223], v155 offset:6144
	ds_read_b128 v[176:179], v155 offset:1024
	ds_read_b128 v[184:187], v155 offset:3072
	ds_read_b128 v[216:219], v155 offset:5120
	ds_read_b128 v[224:227], v155 offset:7168
	global_load_lds_dwordx4 v130, s[8:9]
	s_add_i32 m0, s22, 0xe000
	s_nop 0
	global_load_lds_dwordx4 v150, s[8:9]
	s_waitcnt lgkmcnt(8)
	s_waitcnt vmcnt(10)
	s_barrier
	s_waitcnt lgkmcnt(4)
	s_setprio 1
	v_mfma_f32_16x16x32_bf16 v[124:127], v[156:159], v[172:175], v[124:127]
	v_mfma_f32_16x16x32_bf16 v[120:123], v[164:167], v[172:175], v[120:123]
	v_mfma_f32_16x16x32_bf16 v[116:119], v[156:159], v[180:183], v[116:119]
	v_mfma_f32_16x16x32_bf16 v[108:111], v[164:167], v[180:183], v[108:111]
	v_mfma_f32_16x16x32_bf16 v[100:103], v[156:159], v[188:191], v[100:103]
	v_mfma_f32_16x16x32_bf16 v[92:95], v[164:167], v[188:191], v[92:95]
	v_mfma_f32_16x16x32_bf16 v[84:87], v[156:159], v[220:223], v[84:87]
	v_mfma_f32_16x16x32_bf16 v[76:79], v[164:167], v[220:223], v[76:79]
	s_waitcnt lgkmcnt(0)
	v_mfma_f32_16x16x32_bf16 v[124:127], v[160:163], v[176:179], v[124:127]
	v_mfma_f32_16x16x32_bf16 v[120:123], v[168:171], v[176:179], v[120:123]
	v_mfma_f32_16x16x32_bf16 v[116:119], v[160:163], v[184:187], v[116:119]
	v_mfma_f32_16x16x32_bf16 v[108:111], v[168:171], v[184:187], v[108:111]
	v_mfma_f32_16x16x32_bf16 v[100:103], v[160:163], v[216:219], v[100:103]
	v_mfma_f32_16x16x32_bf16 v[92:95], v[168:171], v[216:219], v[92:95]
	v_mfma_f32_16x16x32_bf16 v[84:87], v[160:163], v[224:227], v[84:87]
	v_mfma_f32_16x16x32_bf16 v[76:79], v[168:171], v[224:227], v[76:79]
	s_setprio 0
	s_barrier
	s_add_i32 s42, 0, 0x14000
	v_add_u32_e32 v152, s42, v154
	s_add_i32 s41, s41, s19
	ds_read_b128 v[228:231], v152
	ds_read_b128 v[236:239], v152 offset:2048
	ds_read_b128 v[232:235], v152 offset:1024
	ds_read_b128 v[240:243], v152 offset:3072
	v_lshl_add_u64 v[152:153], s[12:13], 0, v[132:133]
	s_mov_b32 m0, s41
	v_lshl_add_u64 v[244:245], s[12:13], 0, v[128:129]
	global_load_lds_dwordx4 v132, s[12:13]
	s_add_i32 m0, s41, 0x2000
	s_nop 0
	global_load_lds_dwordx4 v128, s[12:13]
	s_waitcnt vmcnt(10)
	s_barrier
	s_waitcnt lgkmcnt(2)
	s_setprio 1
	v_mfma_f32_16x16x32_bf16 v[112:115], v[228:231], v[172:175], v[112:115]
	v_mfma_f32_16x16x32_bf16 v[104:107], v[236:239], v[172:175], v[104:107]
	v_mfma_f32_16x16x32_bf16 v[96:99], v[228:231], v[180:183], v[96:99]
	v_mfma_f32_16x16x32_bf16 v[88:91], v[236:239], v[180:183], v[88:91]
	v_mfma_f32_16x16x32_bf16 v[80:83], v[228:231], v[188:191], v[80:83]
	v_mfma_f32_16x16x32_bf16 v[72:75], v[236:239], v[188:191], v[72:75]
	v_mfma_f32_16x16x32_bf16 v[68:71], v[228:231], v[220:223], v[68:71]
	v_mfma_f32_16x16x32_bf16 v[64:67], v[236:239], v[220:223], v[64:67]
	s_waitcnt lgkmcnt(0)
	v_mfma_f32_16x16x32_bf16 v[112:115], v[232:235], v[176:179], v[112:115]
	v_mfma_f32_16x16x32_bf16 v[104:107], v[240:243], v[176:179], v[104:107]
	v_mfma_f32_16x16x32_bf16 v[96:99], v[232:235], v[184:187], v[96:99]
	v_mfma_f32_16x16x32_bf16 v[88:91], v[240:243], v[184:187], v[88:91]
	v_mfma_f32_16x16x32_bf16 v[80:83], v[232:235], v[216:219], v[80:83]
	v_mfma_f32_16x16x32_bf16 v[72:75], v[240:243], v[216:219], v[72:75]
	v_mfma_f32_16x16x32_bf16 v[68:71], v[232:235], v[224:227], v[68:71]
	v_mfma_f32_16x16x32_bf16 v[64:67], v[240:243], v[224:227], v[64:67]
	s_setprio 0
	s_mov_b32 m0, s22
	v_lshl_add_u64 v[246:247], s[10:11], 0, v[132:133]
	s_barrier
	ds_read_b128 v[172:175], v155 offset:16384
	ds_read_b128 v[180:183], v155 offset:18432
	ds_read_b128 v[188:191], v155 offset:20480
	ds_read_b128 v[220:223], v155 offset:22528
	ds_read_b128 v[176:179], v155 offset:17408
	ds_read_b128 v[184:187], v155 offset:19456
	ds_read_b128 v[216:219], v155 offset:21504
	ds_read_b128 v[224:227], v155 offset:23552
	global_load_lds_dwordx4 v132, s[10:11]
	v_lshl_add_u64 v[248:249], s[10:11], 0, v[128:129]
	s_mov_b32 m0, s23
	s_nop 0
	global_load_lds_dwordx4 v128, s[10:11]
	s_waitcnt vmcnt(10)
	s_barrier
	s_waitcnt lgkmcnt(4)
	s_setprio 1
	v_mfma_f32_16x16x32_bf16 v[60:63], v[156:159], v[172:175], v[60:63]
	v_mfma_f32_16x16x32_bf16 v[56:59], v[164:167], v[172:175], v[56:59]
	v_mfma_f32_16x16x32_bf16 v[52:55], v[156:159], v[180:183], v[52:55]
	v_mfma_f32_16x16x32_bf16 v[44:47], v[164:167], v[180:183], v[44:47]
	v_mfma_f32_16x16x32_bf16 v[36:39], v[156:159], v[188:191], v[36:39]
	v_mfma_f32_16x16x32_bf16 v[28:31], v[164:167], v[188:191], v[28:31]
	v_mfma_f32_16x16x32_bf16 v[20:23], v[156:159], v[220:223], v[20:23]
	v_mfma_f32_16x16x32_bf16 v[12:15], v[164:167], v[220:223], v[12:15]
	s_waitcnt lgkmcnt(0)
	v_mfma_f32_16x16x32_bf16 v[60:63], v[160:163], v[176:179], v[60:63]
	v_mfma_f32_16x16x32_bf16 v[56:59], v[168:171], v[176:179], v[56:59]
	v_mfma_f32_16x16x32_bf16 v[52:55], v[160:163], v[184:187], v[52:55]
	v_mfma_f32_16x16x32_bf16 v[44:47], v[168:171], v[184:187], v[44:47]
	v_mfma_f32_16x16x32_bf16 v[36:39], v[160:163], v[216:219], v[36:39]
	v_mfma_f32_16x16x32_bf16 v[28:31], v[168:171], v[216:219], v[28:31]
	v_mfma_f32_16x16x32_bf16 v[20:23], v[160:163], v[224:227], v[20:23]
	v_mfma_f32_16x16x32_bf16 v[12:15], v[168:171], v[224:227], v[12:15]
	s_setprio 0
	s_barrier
	s_add_u32 s12, s12, s58
	s_addc_u32 s13, s13, 0
	s_add_i32 s41, s42, s19
	v_lshl_add_u64 v[250:251], s[12:13], 0, v[132:133]
	s_mov_b32 m0, s41
	v_lshl_add_u64 v[252:253], s[12:13], 0, v[128:129]
	global_load_lds_dwordx4 v132, s[12:13]
	s_add_i32 m0, s41, 0x2000
	s_nop 0
	global_load_lds_dwordx4 v128, s[12:13]
	v_add_u32_e32 v168, 0x18000, v154
	ds_read_b128 v[156:159], v168
	ds_read_b128 v[160:163], v168 offset:1024
	ds_read_b128 v[164:167], v168 offset:2048
	ds_read_b128 v[168:171], v168 offset:3072
	s_waitcnt vmcnt(10)
	s_barrier
	s_setprio 1
	v_mfma_f32_16x16x32_bf16 v[48:51], v[228:231], v[172:175], v[48:51]
	v_mfma_f32_16x16x32_bf16 v[40:43], v[236:239], v[172:175], v[40:43]
	v_mfma_f32_16x16x32_bf16 v[32:35], v[228:231], v[180:183], v[32:35]
	v_mfma_f32_16x16x32_bf16 v[24:27], v[236:239], v[180:183], v[24:27]
	v_mfma_f32_16x16x32_bf16 v[16:19], v[228:231], v[188:191], v[16:19]
	v_mfma_f32_16x16x32_bf16 v[8:11], v[236:239], v[188:191], v[8:11]
	v_mfma_f32_16x16x32_bf16 v[4:7], v[228:231], v[220:223], v[4:7]
	v_mfma_f32_16x16x32_bf16 v[0:3], v[236:239], v[220:223], v[0:3]
	v_mfma_f32_16x16x32_bf16 v[48:51], v[232:235], v[176:179], v[48:51]
	v_mfma_f32_16x16x32_bf16 v[40:43], v[240:243], v[176:179], v[40:43]
	v_mfma_f32_16x16x32_bf16 v[32:35], v[232:235], v[184:187], v[32:35]
	v_mfma_f32_16x16x32_bf16 v[24:27], v[240:243], v[184:187], v[24:27]
	v_mfma_f32_16x16x32_bf16 v[16:19], v[232:235], v[216:219], v[16:19]
	v_mfma_f32_16x16x32_bf16 v[8:11], v[240:243], v[216:219], v[8:11]
	v_mfma_f32_16x16x32_bf16 v[4:7], v[232:235], v[224:227], v[4:7]
	v_mfma_f32_16x16x32_bf16 v[0:3], v[240:243], v[224:227], v[0:3]
	s_setprio 0
	s_add_i32 s12, 0, 0x18000
	s_barrier
	s_add_u32 s10, s10, s58
	s_addc_u32 s11, s11, 0
	s_mov_b32 m0, s24
	ds_read_b128 v[172:175], v155 offset:32768
	ds_read_b128 v[180:183], v155 offset:34816
	ds_read_b128 v[188:191], v155 offset:36864
	ds_read_b128 v[220:223], v155 offset:38912
	ds_read_b128 v[176:179], v155 offset:33792
	ds_read_b128 v[184:187], v155 offset:35840
	ds_read_b128 v[216:219], v155 offset:37888
	ds_read_b128 v[224:227], v155 offset:39936
	global_load_lds_dwordx4 v132, s[10:11]
	s_mov_b32 m0, s25
	s_nop 0
	global_load_lds_dwordx4 v128, s[10:11]
	s_waitcnt lgkmcnt(8)
	s_waitcnt vmcnt(10)
	s_barrier
	s_waitcnt lgkmcnt(4)
	s_setprio 1
	v_mfma_f32_16x16x32_bf16 v[124:127], v[156:159], v[172:175], v[124:127]
	v_mfma_f32_16x16x32_bf16 v[120:123], v[164:167], v[172:175], v[120:123]
	v_mfma_f32_16x16x32_bf16 v[116:119], v[156:159], v[180:183], v[116:119]
	v_mfma_f32_16x16x32_bf16 v[108:111], v[164:167], v[180:183], v[108:111]
	v_mfma_f32_16x16x32_bf16 v[100:103], v[156:159], v[188:191], v[100:103]
	v_mfma_f32_16x16x32_bf16 v[92:95], v[164:167], v[188:191], v[92:95]
	v_mfma_f32_16x16x32_bf16 v[84:87], v[156:159], v[220:223], v[84:87]
	v_mfma_f32_16x16x32_bf16 v[76:79], v[164:167], v[220:223], v[76:79]
	s_waitcnt lgkmcnt(0)
	v_mfma_f32_16x16x32_bf16 v[124:127], v[160:163], v[176:179], v[124:127]
	v_mfma_f32_16x16x32_bf16 v[120:123], v[168:171], v[176:179], v[120:123]
	v_mfma_f32_16x16x32_bf16 v[116:119], v[160:163], v[184:187], v[116:119]
	v_mfma_f32_16x16x32_bf16 v[108:111], v[168:171], v[184:187], v[108:111]
	v_mfma_f32_16x16x32_bf16 v[100:103], v[160:163], v[216:219], v[100:103]
	v_mfma_f32_16x16x32_bf16 v[92:95], v[168:171], v[216:219], v[92:95]
	v_mfma_f32_16x16x32_bf16 v[84:87], v[160:163], v[224:227], v[84:87]
	v_mfma_f32_16x16x32_bf16 v[76:79], v[168:171], v[224:227], v[76:79]
	s_setprio 0
	s_barrier
	s_add_i32 s10, 0, 0x1c000
	s_add_i32 s11, s12, s19
	v_add_u32_e32 v200, s10, v154
	v_lshl_add_u64 v[152:153], v[152:153], 0, s[66:67]
	s_mov_b32 m0, s11
	ds_read_b128 v[228:231], v200
	ds_read_b128 v[236:239], v200 offset:2048
	ds_read_b128 v[232:235], v200 offset:1024
	ds_read_b128 v[240:243], v200 offset:3072
	global_load_lds_dwordx4 v[152:153], off
	v_lshl_add_u64 v[152:153], v[244:245], 0, s[66:67]
	s_add_i32 m0, s11, 0x2000
	s_nop 0
	global_load_lds_dwordx4 v[152:153], off
	s_waitcnt vmcnt(10)
	s_barrier
	s_waitcnt lgkmcnt(2)
	s_setprio 1
	v_mfma_f32_16x16x32_bf16 v[112:115], v[228:231], v[172:175], v[112:115]
	v_mfma_f32_16x16x32_bf16 v[104:107], v[236:239], v[172:175], v[104:107]
	v_mfma_f32_16x16x32_bf16 v[96:99], v[228:231], v[180:183], v[96:99]
	v_mfma_f32_16x16x32_bf16 v[88:91], v[236:239], v[180:183], v[88:91]
	v_mfma_f32_16x16x32_bf16 v[80:83], v[228:231], v[188:191], v[80:83]
	v_mfma_f32_16x16x32_bf16 v[72:75], v[236:239], v[188:191], v[72:75]
	v_mfma_f32_16x16x32_bf16 v[68:71], v[228:231], v[220:223], v[68:71]
	v_mfma_f32_16x16x32_bf16 v[64:67], v[236:239], v[220:223], v[64:67]
	s_waitcnt lgkmcnt(0)
	v_mfma_f32_16x16x32_bf16 v[112:115], v[232:235], v[176:179], v[112:115]
	v_mfma_f32_16x16x32_bf16 v[104:107], v[240:243], v[176:179], v[104:107]
	v_mfma_f32_16x16x32_bf16 v[96:99], v[232:235], v[184:187], v[96:99]
	v_mfma_f32_16x16x32_bf16 v[88:91], v[240:243], v[184:187], v[88:91]
	v_mfma_f32_16x16x32_bf16 v[80:83], v[232:235], v[216:219], v[80:83]
	v_mfma_f32_16x16x32_bf16 v[72:75], v[240:243], v[216:219], v[72:75]
	v_mfma_f32_16x16x32_bf16 v[68:71], v[232:235], v[224:227], v[68:71]
	v_mfma_f32_16x16x32_bf16 v[64:67], v[240:243], v[224:227], v[64:67]
	s_setprio 0
	s_mov_b32 m0, s26
	v_lshl_add_u64 v[152:153], v[246:247], 0, s[66:67]
	s_barrier
	ds_read_b128 v[172:175], v155 offset:49152
	ds_read_b128 v[180:183], v155 offset:51200
	ds_read_b128 v[188:191], v155 offset:53248
	ds_read_b128 v[220:223], v155 offset:55296
	ds_read_b128 v[176:179], v155 offset:50176
	ds_read_b128 v[184:187], v155 offset:52224
	ds_read_b128 v[216:219], v155 offset:54272
	ds_read_b128 v[224:227], v155 offset:56320
	global_load_lds_dwordx4 v[152:153], off
	v_lshl_add_u64 v[152:153], v[248:249], 0, s[66:67]
	s_mov_b32 m0, s27
	s_nop 0
	global_load_lds_dwordx4 v[152:153], off
	s_waitcnt vmcnt(10)
	s_barrier
	s_waitcnt lgkmcnt(4)
	s_setprio 1
	v_mfma_f32_16x16x32_bf16 v[60:63], v[156:159], v[172:175], v[60:63]
	v_mfma_f32_16x16x32_bf16 v[56:59], v[164:167], v[172:175], v[56:59]
	v_mfma_f32_16x16x32_bf16 v[52:55], v[156:159], v[180:183], v[52:55]
	v_mfma_f32_16x16x32_bf16 v[44:47], v[164:167], v[180:183], v[44:47]
	v_mfma_f32_16x16x32_bf16 v[36:39], v[156:159], v[188:191], v[36:39]
	v_mfma_f32_16x16x32_bf16 v[28:31], v[164:167], v[188:191], v[28:31]
	v_mfma_f32_16x16x32_bf16 v[20:23], v[156:159], v[220:223], v[20:23]
	v_mfma_f32_16x16x32_bf16 v[12:15], v[164:167], v[220:223], v[12:15]
	s_waitcnt lgkmcnt(0)
	v_mfma_f32_16x16x32_bf16 v[60:63], v[160:163], v[176:179], v[60:63]
	v_mfma_f32_16x16x32_bf16 v[56:59], v[168:171], v[176:179], v[56:59]
	v_mfma_f32_16x16x32_bf16 v[52:55], v[160:163], v[184:187], v[52:55]
	v_mfma_f32_16x16x32_bf16 v[44:47], v[168:171], v[184:187], v[44:47]
	v_mfma_f32_16x16x32_bf16 v[36:39], v[160:163], v[216:219], v[36:39]
	v_mfma_f32_16x16x32_bf16 v[28:31], v[168:171], v[216:219], v[28:31]
	v_mfma_f32_16x16x32_bf16 v[20:23], v[160:163], v[224:227], v[20:23]
	v_mfma_f32_16x16x32_bf16 v[12:15], v[168:171], v[224:227], v[12:15]
	s_setprio 0
	s_barrier
	s_add_i32 s10, s10, s19
	v_lshl_add_u64 v[152:153], v[250:251], 0, s[66:67]
	s_mov_b32 m0, s10
	s_nop 0
	global_load_lds_dwordx4 v[152:153], off
	v_lshl_add_u64 v[152:153], v[252:253], 0, s[66:67]
	s_add_i32 m0, s10, 0x2000
	s_nop 0
	global_load_lds_dwordx4 v[152:153], off
	v_add_u32_e32 v168, 0x10000, v154
	ds_read_b128 v[156:159], v168
	ds_read_b128 v[160:163], v168 offset:1024
	ds_read_b128 v[164:167], v168 offset:2048
	ds_read_b128 v[168:171], v168 offset:3072
	s_waitcnt vmcnt(10)
	s_barrier
	s_setprio 1
	v_mfma_f32_16x16x32_bf16 v[48:51], v[228:231], v[172:175], v[48:51]
	v_mfma_f32_16x16x32_bf16 v[40:43], v[236:239], v[172:175], v[40:43]
	v_mfma_f32_16x16x32_bf16 v[32:35], v[228:231], v[180:183], v[32:35]
	v_mfma_f32_16x16x32_bf16 v[24:27], v[236:239], v[180:183], v[24:27]
	v_mfma_f32_16x16x32_bf16 v[16:19], v[228:231], v[188:191], v[16:19]
	v_mfma_f32_16x16x32_bf16 v[8:11], v[236:239], v[188:191], v[8:11]
	v_mfma_f32_16x16x32_bf16 v[4:7], v[228:231], v[220:223], v[4:7]
	v_mfma_f32_16x16x32_bf16 v[0:3], v[236:239], v[220:223], v[0:3]
	v_mfma_f32_16x16x32_bf16 v[48:51], v[232:235], v[176:179], v[48:51]
	v_mfma_f32_16x16x32_bf16 v[40:43], v[240:243], v[176:179], v[40:43]
	v_mfma_f32_16x16x32_bf16 v[32:35], v[232:235], v[184:187], v[32:35]
	v_mfma_f32_16x16x32_bf16 v[24:27], v[240:243], v[184:187], v[24:27]
	v_mfma_f32_16x16x32_bf16 v[16:19], v[232:235], v[216:219], v[16:19]
	v_mfma_f32_16x16x32_bf16 v[8:11], v[240:243], v[216:219], v[8:11]
	v_mfma_f32_16x16x32_bf16 v[4:7], v[232:235], v[224:227], v[4:7]
	v_mfma_f32_16x16x32_bf16 v[0:3], v[240:243], v[224:227], v[0:3]
	s_setprio 0
	s_add_u32 s8, s8, 0x100
	s_addc_u32 s9, s9, 0
	s_add_u32 s38, s38, 0x100
	s_addc_u32 s39, s39, 0
	s_cmp_ge_u32 s40, s28
	s_mov_b32 s10, s40
	s_barrier
	s_cbranch_scc0 .LBB0_1234
	s_waitcnt lgkmcnt(0)
	v_mov_b32_e32 v152, v135
	s_mov_b64 s[8:9], s[0:1]
	v_readfirstlane_b32 s10, v152
	s_ashr_i32 s12, s10, 2
	s_load_dwordx2 s[8:9], s[8:9], 0x88
	s_lshl_b32 s11, s36, 8
	s_andn2_b32 s12, s12, 63
	s_lshr_b32 s10, s10, 1
	s_add_i32 s12, s12, s11
	s_lshl_b32 s11, s37, 8
	s_and_b32 s10, s10, 0x60
	v_and_or_b32 v156, v152, 15, s12
	s_or_b32 s10, s10, s11
	v_lshrrev_b32_e32 v152, 1, v152
	v_and_or_b32 v152, v152, 24, s10
	v_ashrrev_i32_e32 v153, 31, v152
	s_waitcnt lgkmcnt(0)
	v_lshl_add_u64 v[152:153], v[152:153], 1, s[8:9]
	s_mov_b64 s[8:9], 0x62a4400
	v_ashrrev_i32_e32 v157, 31, v156
	v_lshl_add_u64 v[158:159], v[152:153], 0, s[8:9]
	v_lshlrev_b64 v[152:153], 11, v[156:157]
	v_lshl_add_u64 v[152:153], v[158:159], 0, v[152:153]
	s_mov_b64 s[8:9], 0x40000
	v_cvt_pk_bf16_f32 v68, v68, v69
	v_cvt_pk_bf16_f32 v69, v70, v71
	v_cvt_pk_bf16_f32 v70, v64, v65
	v_lshl_add_u64 v[64:65], v[152:153], 0, s[8:9]
	s_mov_b32 s8, 0x40000
	v_cvt_pk_bf16_f32 v60, v60, v61
	v_cvt_pk_bf16_f32 v61, v62, v63
	v_cvt_pk_bf16_f32 v62, v56, v57
	v_add_co_u32_e32 v56, vcc, s8, v152
	v_cvt_pk_bf16_f32 v48, v48, v49
	v_cvt_pk_bf16_f32 v49, v50, v51
	s_mov_b64 s[8:9], 0x48000
	s_nop 0
	v_addc_co_u32_e32 v57, vcc, 0, v153, vcc
	v_cvt_pk_bf16_f32 v50, v40, v41
	v_cvt_pk_bf16_f32 v51, v42, v43
	global_store_dwordx4 v[64:65], v[48:51], off offset:256 sc1
	v_cvt_pk_bf16_f32 v42, v44, v45
	v_cvt_pk_bf16_f32 v32, v32, v33
	v_cvt_pk_bf16_f32 v33, v34, v35
	v_cvt_pk_bf16_f32 v112, v112, v113
	v_cvt_pk_bf16_f32 v113, v114, v115
	s_nop 1
	v_lshl_add_u64 v[48:49], v[152:153], 0, s[8:9]
	s_mov_b32 s8, 0x48000
	v_add_co_u32_e32 v44, vcc, s8, v152
	s_mov_b64 s[8:9], 0x50000
	v_cvt_pk_bf16_f32 v114, v104, v105
	v_or_b32_e32 v104, 16, v156
	v_addc_co_u32_e32 v45, vcc, 0, v153, vcc
	v_cvt_pk_bf16_f32 v34, v24, v25
	v_cvt_pk_bf16_f32 v35, v26, v27
	global_store_dwordx4 v[48:49], v[32:35], off offset:256 sc1
	v_ashrrev_i32_e32 v105, 31, v104
	v_cvt_pk_bf16_f32 v96, v96, v97
	v_cvt_pk_bf16_f32 v97, v98, v99
	v_cvt_pk_bf16_f32 v98, v88, v89
	v_or_b32_e32 v88, 32, v156
	v_lshl_add_u64 v[32:33], v[152:153], 0, s[8:9]
	s_mov_b32 s8, 0x50000
	v_cvt_pk_bf16_f32 v26, v28, v29
	v_add_co_u32_e32 v28, vcc, s8, v152
	v_cvt_pk_bf16_f32 v16, v16, v17
	v_cvt_pk_bf16_f32 v17, v18, v19
	s_mov_b64 s[8:9], 0x58000
	v_lshlrev_b64 v[104:105], 11, v[104:105]
	v_ashrrev_i32_e32 v89, 31, v88
	v_cvt_pk_bf16_f32 v80, v80, v81
	v_cvt_pk_bf16_f32 v81, v82, v83
	v_cvt_pk_bf16_f32 v82, v72, v73
	v_or_b32_e32 v72, 48, v156
	v_addc_co_u32_e32 v29, vcc, 0, v153, vcc
	v_cvt_pk_bf16_f32 v18, v8, v9
	v_cvt_pk_bf16_f32 v19, v10, v11
	global_store_dwordx4 v[32:33], v[16:19], off offset:256 sc1
	v_cvt_pk_bf16_f32 v115, v106, v107
	global_store_dwordx4 v[152:153], v[112:115], off offset:256 sc1
	v_lshlrev_b64 v[88:89], 11, v[88:89]
	v_lshl_add_u64 v[16:17], v[152:153], 0, s[8:9]
	s_mov_b32 s8, 0x58000
	v_lshl_add_u64 v[112:113], v[158:159], 0, v[104:105]
	v_ashrrev_i32_e32 v73, 31, v72
	v_cvt_pk_bf16_f32 v10, v12, v13
	v_add_co_u32_e32 v12, vcc, s8, v152
	v_cvt_pk_bf16_f32 v99, v90, v91
	global_store_dwordx4 v[112:113], v[96:99], off offset:256 sc1
	v_lshlrev_b64 v[72:73], 11, v[72:73]
	v_addc_co_u32_e32 v13, vcc, 0, v153, vcc
	v_lshl_add_u64 v[96:97], v[158:159], 0, v[88:89]
	v_cvt_pk_bf16_f32 v83, v74, v75
	global_store_dwordx4 v[96:97], v[80:83], off offset:256 sc1
	s_and_b64 vcc, exec, s[4:5]
	s_mov_b32 s37, s34
	v_lshl_add_u64 v[80:81], v[158:159], 0, v[72:73]
	s_mov_b32 s36, s35
	s_mov_b64 s[10:11], s[6:7]
	s_mov_b64 s[12:13], s[2:3]
	v_cvt_pk_bf16_f32 v124, v124, v125
	v_cvt_pk_bf16_f32 v125, v126, v127
	v_cvt_pk_bf16_f32 v126, v120, v121
	v_cvt_pk_bf16_f32 v127, v122, v123
	global_store_dwordx4 v[152:153], v[124:127], off sc1
	v_cvt_pk_bf16_f32 v104, v116, v117
	v_cvt_pk_bf16_f32 v105, v118, v119
	v_cvt_pk_bf16_f32 v106, v108, v109
	v_cvt_pk_bf16_f32 v107, v110, v111
	global_store_dwordx4 v[112:113], v[104:107], off sc1
	v_cvt_pk_bf16_f32 v88, v100, v101
	v_cvt_pk_bf16_f32 v89, v102, v103
	v_cvt_pk_bf16_f32 v90, v92, v93
	v_cvt_pk_bf16_f32 v91, v94, v95
	global_store_dwordx4 v[96:97], v[88:91], off sc1
	v_cvt_pk_bf16_f32 v72, v84, v85
	v_cvt_pk_bf16_f32 v73, v86, v87
	v_cvt_pk_bf16_f32 v74, v76, v77
	v_cvt_pk_bf16_f32 v75, v78, v79
	global_store_dwordx4 v[80:81], v[72:75], off sc1
	v_cvt_pk_bf16_f32 v71, v66, v67
	global_store_dwordx4 v[80:81], v[68:71], off offset:256 sc1
	v_cvt_pk_bf16_f32 v63, v58, v59
	global_store_dwordx4 v[56:57], v[60:63], off sc1
	v_cvt_pk_bf16_f32 v40, v52, v53
	v_cvt_pk_bf16_f32 v41, v54, v55
	v_cvt_pk_bf16_f32 v43, v46, v47
	global_store_dwordx4 v[44:45], v[40:43], off sc1
	v_cvt_pk_bf16_f32 v24, v36, v37
	v_cvt_pk_bf16_f32 v25, v38, v39
	v_cvt_pk_bf16_f32 v27, v30, v31
	global_store_dwordx4 v[28:29], v[24:27], off sc1
	v_cvt_pk_bf16_f32 v8, v20, v21
	v_cvt_pk_bf16_f32 v9, v22, v23
	v_cvt_pk_bf16_f32 v11, v14, v15
	global_store_dwordx4 v[12:13], v[8:11], off sc1
	v_cvt_pk_bf16_f32 v4, v4, v5
	v_cvt_pk_bf16_f32 v5, v6, v7
	v_cvt_pk_bf16_f32 v6, v0, v1
	v_cvt_pk_bf16_f32 v7, v2, v3
	global_store_dwordx4 v[16:17], v[4:7], off offset:256 sc1
	s_cbranch_vccz .LBB0_1223
	s_waitcnt vmcnt(0)
	s_cmpk_gt_u32 s14, 0xff
	s_cbranch_scc1 .LBB0_1238
	s_barrier
